# EpiRes hoisted loads + nt stores in EpiScale epilogue + hand-pipelined attention tile loop (QK of next tile and softmax interleaved with PV MFMAs) + head-major attention work order
# speedup vs baseline: 1.0027x; 1.0027x over previous
; DI void attn_unit(const bf16_t* z, const bf16_t* VT, bf16_t* Y, const float* subg, ldsp lds, int tid, int b, int h, int qb, float lam, float ns, float oscale, int win) {
;     ...
;     bf16x8 qf[2][2];
; #pragma unroll
;     for (int qt = 0; qt < 2; ++qt)
; #pragma unroll
;         for (int ks = 0; ks < 2; ++ks) qf[qt][ks] = *(const bf16x8*)(z + (size_t)(b * SEQ + q0 + 16 * qt + fr) * ZLD + C_DQ + h * 128 + comp * 64 + 32 * ks + 8 * fq);
;     f32x4 O[8][2];
; #pragma unroll
;     for (int e = 0; e < 8; ++e)
; #pragma unroll
;         for (int qt = 0; qt < 2; ++qt) O[e][qt] = (f32x4){0.f, 0.f, 0.f, 0.f};
;     float ls0 = 0.f, ls1 = 0.f;
;     const float tq0 = (float)(q0 + fr), tq1 = tq0 + 16.0f;
;     const int kr = 4 * w + (lane >> 4), vr = 8 * w + (lane >> 3);
;     const bf16_t* kg = z + (size_t)(b * SEQ + kr) * ZLD + C_DK + h * 128 + (((lane & 15) ^ (kr & 15)) * 8);
;     const bf16_t* vg = VT + (size_t)((b * 4 + h) * 128 + vr) * SEQ + (((lane & 7) ^ ((vr >> 1) & 7)) * 8);
;     ...
;     int koff[2], voff[2];
; #pragma unroll
;     for (int ks = 0; ks < 2; ++ks) koff[ks] = fr * 256 + (((comp * 8 + 4 * ks + fq) ^ fr) * 16);
; #pragma unroll
;     for (int m = 0; m < 2; ++m) voff[m] = AT_KT + fr * 128 + (((4 * m + fq) ^ ((fr >> 1) & 7)) * 16);
;     __syncthreads();
;     AT_DMA(jstart, jstart & 1);
;     asm volatile("s_waitcnt vmcnt(0)" ::: "memory");
;     __syncthreads();
; __global__ void __launch_bounds__(512, 2) hybrid_fwd(Args a) {
;     ...
;                         const int r = 63 - (xq & 1) - 2 * (idx >> 2), h = idx & 3, b = xq >> 1;
;                         const float slope = exp2f(-2.0f * (float)(h + 1));
;                         const float wf = (104.0f + 2.0f * smax) / slope;
;                         const int win = wf < 16384.0f ? (int)wf + 1 : 16384;
;                         attn_unit(Z, VT, Y, a.diff_subln_g + l * 128, lds, tu, b, h, r, lam, -slope * LOG2E, 1.0f - lam_init, win);
.LBB0_410:
	s_andn2_b64 vcc, exec, s[0:1]
	s_cbranch_vccnz .LBB0_401
	s_lshr_b32 s12, s28, 5
	s_sub_i32 s12, 3, s12
	s_not_b32 s0, s12
	s_lshl_b32 s0, s0, 1
	v_ldexp_f32 v85, 1.0, s0
	v_div_scale_f32 v0, s[0:1], v85, v85, v175
	v_rcp_f32_e32 v1, v0
	v_div_scale_f32 v2, vcc, v175, v85, v175
	s_and_b32 s0, s28, 31
	v_fma_f32 v3, -v0, v1, 1.0
	v_fmac_f32_e32 v1, v3, v1
	v_mul_f32_e32 v3, v2, v1
	v_fma_f32 v4, -v0, v3, v2
	v_fmac_f32_e32 v3, v4, v1
	v_fma_f32 v0, -v0, v3, v2
	v_div_fmas_f32 v0, v0, v1, v3
	v_div_fixup_f32 v0, v0, v85, v175
	v_cvt_i32_f32_e32 v1, v0
	s_lshl_b32 s0, s0, 1
	s_sub_i32 s14, s84, s0
	s_mov_b32 s0, 0x46800000
	v_cmp_gt_f32_e32 vcc, s0, v0
	v_readfirstlane_b32 s0, v80
	s_ashr_i32 s8, s0, 7
	v_add_u32_e32 v1, 1, v1
	s_lshl_b32 s6, s14, 7
	s_lshl_b32 s1, s8, 5
	v_cndmask_b32_e32 v86, v211, v1, vcc
	s_add_i32 s1, s1, s6
	v_sub_u32_e32 v0, s6, v86
	s_add_i32 s6, s1, s85
	s_ashr_i32 s15, s0, 6
	v_ashrrev_i32_e32 v4, 6, v0
	v_or_b32_e32 v120, s6, v81
	v_mov_b64_e32 v[0:1], s[70:71]
	s_and_b32 s9, s15, 1
	v_mad_i64_i32 v[2:3], s[10:11], v120, s97, v[0:1]
	s_lshl_b32 s30, s12, 8
	v_lshl_add_u64 v[2:3], v[2:3], 0, s[30:31]
	s_lshl_b32 s10, s9, 7
	s_mov_b32 s11, s31
	v_lshl_add_u64 v[2:3], v[2:3], 0, s[10:11]
	v_and_b32_e32 v156, 48, v80
	v_lshl_add_u64 v[2:3], v[2:3], 0, v[156:157]
	v_or_b32_e32 v118, 16, v120
	s_lshl_b32 s6, s12, 7
	global_load_dwordx4 v[56:59], v[2:3], off offset:1536
	global_load_dwordx4 v[60:63], v[2:3], off offset:1600
	v_mad_i64_i32 v[2:3], s[12:13], v118, s97, v[0:1]
	v_lshl_add_u64 v[2:3], v[2:3], 0, s[30:31]
	v_lshl_add_u64 v[2:3], v[2:3], 0, s[10:11]
	v_lshl_add_u64 v[2:3], v[2:3], 0, v[156:157]
	s_lshl_b32 s12, s15, 2
	global_load_dwordx4 v[64:67], v[2:3], off offset:1536
	global_load_dwordx4 v[68:71], v[2:3], off offset:1600
	v_or_b32_e32 v2, s12, v177
	v_add_u32_e32 v2, s85, v2
	v_bfe_u32 v3, v80, 3, 3
	v_mad_i64_i32 v[0:1], s[10:11], v2, s97, v[0:1]
	v_lshl_or_b32 v5, s15, 3, v3
	v_bitop3_b32 v6, s12, v80, v177 bitop3:0x36
	s_or_b32 s10, s6, s86
	v_add_u32_e32 v2, s10, v5
	v_lshrrev_b32_e32 v5, 1, v5
	v_lshlrev_b32_e32 v6, 4, v6
	v_max_i32_e32 v84, 0, v4
	v_xor_b32_e32 v5, v5, v80
	v_lshl_add_u64 v[0:1], v[0:1], 0, s[30:31]
	v_and_b32_e32 v156, 0xf0, v6
	v_ashrrev_i32_e32 v3, 31, v2
	v_lshl_add_u64 v[122:123], v[0:1], 0, v[156:157]
	v_lshlrev_b32_e32 v0, 4, v5
	v_lshlrev_b32_e32 v82, 6, v84
	v_lshlrev_b64 v[2:3], 14, v[2:3]
	v_and_b32_e32 v156, 0x70, v0
	v_mad_u64_u32 v[0:1], s[10:11], v82, s97, v[122:123]
	v_lshl_add_u64 v[2:3], s[62:63], 0, v[2:3]
	v_lshlrev_b32_e32 v83, 15, v84
	s_lshl_b32 s10, s15, 10
	v_lshl_add_u64 v[124:125], v[2:3], 0, v[156:157]
	v_and_b32_e32 v2, 0x8000, v83
	s_add_i32 s10, s10, 0
	v_add_u32_e32 v2, s10, v2
	v_lshl_add_u64 v[0:1], v[0:1], 0, s[18:19]
	v_readfirstlane_b32 s11, v2
	s_mov_b32 m0, s11
	s_barrier
	global_load_lds_dwordx4 v[0:1], off
	v_or_b32_e32 v0, 32, v82
	v_add_u32_e32 v3, 0x2000, v2
	v_mad_u64_u32 v[0:1], s[12:13], v0, s97, v[122:123]
	v_readfirstlane_b32 s11, v3
	v_add_u32_e32 v3, 0x4000, v2
	v_lshl_add_u64 v[0:1], v[0:1], 0, s[18:19]
	s_mov_b32 m0, s11
	v_lshlrev_b32_e32 v156, 7, v84
	v_readfirstlane_b32 s11, v3
	s_mov_b64 s[12:13], 0x100000
	v_add_u32_e32 v2, 0x6000, v2
	global_load_lds_dwordx4 v[0:1], off
	v_lshl_add_u64 v[0:1], v[124:125], 0, v[156:157]
	s_mov_b32 m0, s11
	v_lshl_add_u64 v[126:127], v[124:125], 0, s[12:13]
	v_readfirstlane_b32 s11, v2
	global_load_lds_dwordx4 v[0:1], off
	v_lshl_add_u64 v[0:1], v[126:127], 0, v[156:157]
	s_mov_b32 m0, s11
	s_lshl_b32 s12, s14, 1
	global_load_lds_dwordx4 v[0:1], off
	s_waitcnt vmcnt(0)
	s_add_i32 s11, s12, 2
	v_mov_b32_e32 v129, 0
	v_cmp_gt_i32_e32 vcc, s11, v4
	v_mov_b32_e32 v128, v129
	v_mov_b32_e32 v3, v129
	v_mov_b32_e32 v2, v129
	v_mov_b32_e32 v1, v129
	v_mov_b32_e32 v0, v129
	v_mov_b32_e32 v7, v129
	v_mov_b32_e32 v6, v129
	v_mov_b32_e32 v5, v129
	v_mov_b32_e32 v4, v129
	v_mov_b32_e32 v11, v129
	v_mov_b32_e32 v10, v129
	v_mov_b32_e32 v9, v129
	v_mov_b32_e32 v8, v129
	v_mov_b32_e32 v27, v129
	v_mov_b32_e32 v26, v129
	v_mov_b32_e32 v25, v129
	v_mov_b32_e32 v24, v129
	v_mov_b32_e32 v75, v129
	v_mov_b32_e32 v74, v129
	v_mov_b32_e32 v73, v129
	v_mov_b32_e32 v72, v129
	v_mov_b32_e32 v79, v129
	v_mov_b32_e32 v78, v129
	v_mov_b32_e32 v77, v129
	v_mov_b32_e32 v76, v129
	v_mov_b32_e32 v55, v129
	v_mov_b32_e32 v54, v129
	v_mov_b32_e32 v53, v129
	v_mov_b32_e32 v52, v129
	v_mov_b32_e32 v51, v129
	v_mov_b32_e32 v50, v129
	v_mov_b32_e32 v49, v129
	v_mov_b32_e32 v48, v129
	v_mov_b32_e32 v47, v129
	v_mov_b32_e32 v46, v129
	v_mov_b32_e32 v45, v129
	v_mov_b32_e32 v44, v129
	v_mov_b32_e32 v43, v129
	v_mov_b32_e32 v42, v129
	v_mov_b32_e32 v41, v129
	v_mov_b32_e32 v40, v129
	v_mov_b32_e32 v39, v129
	v_mov_b32_e32 v38, v129
	v_mov_b32_e32 v37, v129
	v_mov_b32_e32 v36, v129
	v_mov_b32_e32 v35, v129
	v_mov_b32_e32 v34, v129
	v_mov_b32_e32 v33, v129
	v_mov_b32_e32 v32, v129
	v_mov_b32_e32 v31, v129
	v_mov_b32_e32 v30, v129
	v_mov_b32_e32 v29, v129
	v_mov_b32_e32 v28, v129
	v_mov_b32_e32 v23, v129
	v_mov_b32_e32 v22, v129
	v_mov_b32_e32 v21, v129
	v_mov_b32_e32 v20, v129
	v_mov_b32_e32 v19, v129
	v_mov_b32_e32 v18, v129
	v_mov_b32_e32 v17, v129
	v_mov_b32_e32 v16, v129
	v_mov_b32_e32 v15, v129
	v_mov_b32_e32 v14, v129
	v_mov_b32_e32 v13, v129
	v_mov_b32_e32 v12, v129
	s_waitcnt vmcnt(0) lgkmcnt(0)
	s_barrier
; DI void attn_unit(const bf16_t* z, const bf16_t* VT, bf16_t* Y, const float* subg, ldsp lds, int tid, int b, int h, int qb, float lam, float ns, float oscale, int win) {
;     ...
;     for (int j = jstart; j < nt; ++j) {
;         if (j + 1 < nt) AT_DMA(j + 1, (j + 1) & 1);
;         if (j <= wlast && j >= wfirst) {
;             const ldsp sb = lds + (j & 1) * AT_STG;
	s_and_saveexec_b64 s[28:29], vcc
	s_cbranch_execz .LBB0_419
	s_ashr_i32 s0, s0, 8
	s_add_i32 s12, s0, s12
	v_or_b32_e32 v1, s1, v81
	s_lshl_b32 s0, s9, 3
	v_sub_u32_e32 v0, s1, v86
	v_cvt_f32_i32_e32 v121, v1
	v_or_b32_e32 v1, s0, v177
	v_bitop3_b32 v1, v1, v81, 4 bitop3:0x36
	v_ashrrev_i32_e32 v182, 6, v0
	v_lshrrev_b32_e32 v0, 1, v80
	v_lshlrev_b32_e32 v181, 4, v1
	v_bfe_u32 v1, v80, 1, 3
	v_bitop3_b32 v0, v177, v0, 7 bitop3:0x78
	v_bitop3_b32 v2, s0, v81, v177 bitop3:0x36
	v_lshlrev_b32_e32 v184, 4, v0
	v_bitop3_b32 v0, v177, v1, 4 bitop3:0x36
	v_mov_b32_e32 v12, 0
	v_mul_f32_e32 v119, 0xbfb8aa3b, v85
	v_lshlrev_b32_e32 v179, 8, v81
	v_lshlrev_b32_e32 v180, 4, v2
	v_lshlrev_b32_e32 v183, 7, v81
	v_lshlrev_b32_e32 v185, 4, v0
	v_add_f32_e32 v186, 0x41800000, v121
	v_lshlrev_b32_e32 v187, 2, v177
	s_mov_b64 s[74:75], 0
	v_mov_b32_e32 v13, v12
	v_mov_b32_e32 v14, v12
	v_mov_b32_e32 v15, v12
	v_mov_b32_e32 v16, v12
	v_mov_b32_e32 v17, v12
	v_mov_b32_e32 v18, v12
	v_mov_b32_e32 v19, v12
	v_mov_b32_e32 v20, v12
	v_mov_b32_e32 v21, v12
	v_mov_b32_e32 v22, v12
	v_mov_b32_e32 v23, v12
	v_mov_b32_e32 v28, v12
	v_mov_b32_e32 v29, v12
	v_mov_b32_e32 v30, v12
	v_mov_b32_e32 v31, v12
	v_mov_b32_e32 v32, v12
	v_mov_b32_e32 v33, v12
	v_mov_b32_e32 v34, v12
	v_mov_b32_e32 v35, v12
	v_mov_b32_e32 v36, v12
	v_mov_b32_e32 v37, v12
	v_mov_b32_e32 v38, v12
	v_mov_b32_e32 v39, v12
	v_mov_b32_e32 v40, v12
	v_mov_b32_e32 v41, v12
	v_mov_b32_e32 v42, v12
	v_mov_b32_e32 v43, v12
	v_mov_b32_e32 v44, v12
	v_mov_b32_e32 v45, v12
	v_mov_b32_e32 v46, v12
	v_mov_b32_e32 v47, v12
	v_mov_b32_e32 v48, v12
	v_mov_b32_e32 v49, v12
	v_mov_b32_e32 v50, v12
	v_mov_b32_e32 v51, v12
	v_mov_b32_e32 v52, v12
	v_mov_b32_e32 v53, v12
	v_mov_b32_e32 v54, v12
	v_mov_b32_e32 v55, v12
	v_mov_b32_e32 v76, v12
	v_mov_b32_e32 v77, v12
	v_mov_b32_e32 v78, v12
	v_mov_b32_e32 v79, v12
	v_mov_b32_e32 v72, v12
	v_mov_b32_e32 v73, v12
	v_mov_b32_e32 v74, v12
	v_mov_b32_e32 v75, v12
	v_mov_b32_e32 v24, v12
	v_mov_b32_e32 v25, v12
	v_mov_b32_e32 v26, v12
	v_mov_b32_e32 v27, v12
	v_mov_b32_e32 v8, v12
	v_mov_b32_e32 v9, v12
	v_mov_b32_e32 v10, v12
	v_mov_b32_e32 v11, v12
	v_mov_b32_e32 v4, v12
	v_mov_b32_e32 v5, v12
	v_mov_b32_e32 v6, v12
	v_mov_b32_e32 v7, v12
	v_mov_b32_e32 v0, v12
	v_mov_b32_e32 v1, v12
	v_mov_b32_e32 v2, v12
	v_mov_b32_e32 v3, v12
	v_mov_b32_e32 v128, v12
	v_mov_b32_e32 v129, v12
	v_readfirstlane_b32 s74, v84
	v_readfirstlane_b32 s75, v182
	v_add_u32_e32 v130, v179, v180
	v_add_u32_e32 v131, v179, v181
	v_add_u32_e32 v132, v183, v184
	v_add_u32_e32 v133, v183, v185
	v_add_u32_e32 v132, 0x4000, v132
	v_add_u32_e32 v133, 0x4000, v133
	s_mov_b32 s43, s74
	s_max_i32 s75, s75, s74
	s_add_i32 s42, s11, -1
	s_min_i32 s42, s42, s12
	s_add_i32 s74, s74, -1
	s_and_b32 s101, s43, 1
.Lat_loop:
	s_lshl_b32 s1, s101, 15
	s_add_i32 s14, s101, 1
	s_cmp_ge_i32 s14, 2
	s_cselect_b32 s0, 2, 0
	s_sub_i32 s14, s14, s0
	s_lshl_b32 s14, s14, 15
	v_add_u32_e32 v134, s1, v130
	v_add_u32_e32 v135, s1, v131
	v_add_u32_e32 v138, s14, v132
	v_add_u32_e32 v139, s14, v133
	s_add_i32 s0, s74, 1
	s_cmp_ge_i32 s0, s75
	s_cselect_b32 s1, 1, 0
	s_cmp_le_i32 s0, s42
	s_cselect_b32 s14, 1, 0
	s_and_b32 s1, s1, s14
	s_cmp_ge_i32 s74, s75
	s_cselect_b32 s14, 2, 0
	s_cmp_le_i32 s74, s42
	s_cselect_b32 s15, 2, 0
	s_and_b32 s14, s14, s15
	s_or_b32 s1, s1, s14
	s_cmp_eq_u32 s1, 3
	s_cbranch_scc1 .Lat_both
	s_cmp_eq_u32 s1, 1
	s_cbranch_scc1 .Lat_qk
	s_cmp_eq_u32 s1, 2
	s_cbranch_scc1 .Lat_pv
	s_add_i32 s0, s74, 2
	s_cmp_lt_i32 s0, s11
	s_cbranch_scc0 .Lat_nok_n
	s_mul_i32 s14, s0, 0x70000
	s_add_i32 s14, s14, 0xa00
	s_mov_b32 s15, 0
	v_lshl_add_u64 v[214:215], v[122:123], 0, s[14:15]
	s_add_i32 s1, s101, 1
	s_cmp_ge_i32 s1, 2
	s_cselect_b32 s0, 2, 0
	s_sub_i32 s1, s1, s0
	s_lshl_b32 s1, s1, 15
	s_add_i32 s1, s1, s10
	s_mov_b32 m0, s1
	s_add_i32 s14, s14, 0x38000
	global_load_lds_dwordx4 v[214:215], off
	v_lshl_add_u64 v[80:81], v[122:123], 0, s[14:15]
	s_add_i32 m0, s1, 0x2000
	s_nop 0
	global_load_lds_dwordx4 v[80:81], off
.Lat_nok_n:
	s_add_i32 s0, s74, 1
	s_cmp_lt_i32 s0, s11
	s_cbranch_scc0 .Lat_nov_n
	s_cmp_gt_i32 s0, s43
	s_cbranch_scc0 .Lat_nov_n
	s_lshl_b32 s14, s0, 7
	s_mov_b32 s15, 0
	v_lshl_add_u64 v[214:215], v[124:125], 0, s[14:15]
	v_lshl_add_u64 v[80:81], v[126:127], 0, s[14:15]
	s_add_i32 s1, s101, 0
	s_cmp_ge_i32 s1, 2
	s_cselect_b32 s0, 2, 0
	s_sub_i32 s1, s1, s0
	s_lshl_b32 s1, s1, 15
	s_add_i32 s1, s1, s10
	s_add_i32 m0, s1, 0x4000
	s_nop 0
	global_load_lds_dwordx4 v[214:215], off
	s_add_i32 m0, s1, 0x6000
	s_nop 0
	global_load_lds_dwordx4 v[80:81], off

; #define LAS __attribute__((address_space(3)))
; #define LAS __attribute__((address_space(3)))
; #define MFMA16(a, b, c) __builtin_amdgcn_mfma_f32_16x16x32_bf16((a), (b), (c), 0, 0, 0)
; DI void attn_unit(const bf16_t* z, const bf16_t* VT, bf16_t* Y, const float* subg, ldsp lds, int tid, int b, int h, int qb, float lam, float ns, float oscale, int win) {
;     ...
;             for (int ks = 0; ks < 2; ++ks) {
;                 bf16x8 kf[4];
; #pragma unroll
;                 for (int kt = 0; kt < 4; ++kt) kf[kt] = *(LAS bf16x8*)(sb + koff[ks] + kt * 4096);
; #pragma unroll
;                 for (int kt = 0; kt < 4; ++kt)
; #pragma unroll
;                     for (int qt = 0; qt < 2; ++qt) S[kt][qt] = MFMA16(kf[kt], qf[qt][ks], S[kt][qt]);
;             }
;             const float dl0 = (float)(64 * j + 4 * fq) - tq0, dl1 = (float)(64 * j + 4 * fq) - tq1;
; #pragma unroll
;             for (int m = 0; m < 2; ++m) {
;                 bf16x8 vf[8];
; #pragma unroll
;                 for (int et = 0; et < 8; ++et) vf[et] = *(LAS bf16x8*)(sb + voff[m] + et * 2048);
.Lat_both:
	ds_read_b128 v[216:219], v134
	ds_read_b128 v[220:223], v134 offset:4096
	ds_read_b128 v[224:227], v134 offset:8192
	ds_read_b128 v[228:231], v134 offset:12288
	ds_read_b128 v[232:235], v135
	ds_read_b128 v[236:239], v135 offset:4096
	ds_read_b128 v[240:243], v135 offset:8192
	ds_read_b128 v[244:247], v135 offset:12288
	ds_read_b128 v[164:167], v138
	ds_read_b128 v[168:171], v138 offset:2048
	ds_read_b128 v[188:191], v138 offset:4096
	ds_read_b128 v[192:195], v138 offset:6144
	s_add_i32 s0, s74, 2
	s_cmp_lt_i32 s0, s11
	s_cbranch_scc0 .Lat_nok_b
	s_mul_i32 s14, s0, 0x70000
	s_add_i32 s14, s14, 0xa00
	s_mov_b32 s15, 0
	v_lshl_add_u64 v[214:215], v[122:123], 0, s[14:15]
	s_add_i32 s1, s101, 1
	s_cmp_ge_i32 s1, 2
	s_cselect_b32 s0, 2, 0
	s_sub_i32 s1, s1, s0
	s_lshl_b32 s1, s1, 15
	s_add_i32 s1, s1, s10
	s_mov_b32 m0, s1
	s_add_i32 s14, s14, 0x38000
	global_load_lds_dwordx4 v[214:215], off
	v_lshl_add_u64 v[80:81], v[122:123], 0, s[14:15]
	s_add_i32 m0, s1, 0x2000
	s_nop 0
	global_load_lds_dwordx4 v[80:81], off

; #define LAS __attribute__((address_space(3)))
; #define LAS __attribute__((address_space(3)))
; DI unsigned pk(float lo, float hi) { return pg8::cvt_pk_bf16(lo, hi); }
; #define MFMA16(a, b, c) __builtin_amdgcn_mfma_f32_16x16x32_bf16((a), (b), (c), 0, 0, 0)
; DI void attn_unit(const bf16_t* z, const bf16_t* VT, bf16_t* Y, const float* subg, ldsp lds, int tid, int b, int h, int qb, float lam, float ns, float oscale, int win) {
;     ...
;             for (int ks = 0; ks < 2; ++ks) {
;                 bf16x8 kf[4];
; #pragma unroll
;                 for (int kt = 0; kt < 4; ++kt) kf[kt] = *(LAS bf16x8*)(sb + koff[ks] + kt * 4096);
; #pragma unroll
;                 for (int kt = 0; kt < 4; ++kt)
; #pragma unroll
;                     for (int qt = 0; qt < 2; ++qt) S[kt][qt] = MFMA16(kf[kt], qf[qt][ks], S[kt][qt]);
;             }
;             const float dl0 = (float)(64 * j + 4 * fq) - tq0, dl1 = (float)(64 * j + 4 * fq) - tq1;
; #pragma unroll
;             for (int m = 0; m < 2; ++m) {
;                 bf16x8 vf[8];
; #pragma unroll
;                 for (int et = 0; et < 8; ++et) vf[et] = *(LAS bf16x8*)(sb + voff[m] + et * 2048);
;                 bf16x8 pf[2];
; #pragma unroll
;                 for (int qt = 0; qt < 2; ++qt) {
;                     const float dl = qt ? dl1 : dl0;
;                     float p[8];
; #pragma unroll
;                     for (int i = 0; i < 8; ++i) {
;                         const int kt = 2 * m + (i >> 2), r = i & 3;
;                         p[i] = __builtin_amdgcn_exp2f(fmaf(fabsf(dl + (float)(16 * kt + r)), ns, S[kt][qt][r]));
;                     }
;                     const float sum = ((p[0] + p[1]) + (p[2] + p[3])) + ((p[4] + p[5]) + (p[6] + p[7]));
;                     if (qt) ls1 += sum; else ls0 += sum;
;                     u32x4 u; u.x = pk(p[0], p[1]); u.y = pk(p[2], p[3]); u.z = pk(p[4], p[5]); u.w = pk(p[6], p[7]);
;                     pf[qt] = __builtin_bit_cast(bf16x8, u);
;                 }
; #pragma unroll
;                 for (int et = 0; et < 8; ++et)
; #pragma unroll
;                     for (int qt = 0; qt < 2; ++qt) O[et][qt] = MFMA16(vf[et], pf[qt], O[et][qt]);
.Lat_nov_b:
	v_cvt_pk_bf16_f32 v140, v84, v85
	v_cvt_pk_bf16_f32 v141, v86, v87
	v_cvt_pk_bf16_f32 v142, v92, v93
	v_cvt_pk_bf16_f32 v143, v94, v95
	v_cvt_pk_bf16_f32 v144, v88, v89
	v_cvt_pk_bf16_f32 v145, v90, v91
	v_cvt_pk_bf16_f32 v146, v96, v97
	v_cvt_pk_bf16_f32 v147, v98, v99
	v_cvt_pk_bf16_f32 v148, v100, v101
	v_cvt_pk_bf16_f32 v149, v102, v103
	v_cvt_pk_bf16_f32 v150, v108, v109
	v_cvt_pk_bf16_f32 v151, v110, v111
	v_cvt_pk_bf16_f32 v152, v104, v105
	v_cvt_pk_bf16_f32 v153, v106, v107
	v_cvt_pk_bf16_f32 v154, v112, v113
	v_cvt_pk_bf16_f32 v155, v114, v115
	s_waitcnt lgkmcnt(8)
	v_mfma_f32_16x16x32_bf16 v[84:87], v[216:219], v[56:59], 0
	v_mfma_f32_16x16x32_bf16 v[88:91], v[216:219], v[64:67], 0
	v_mfma_f32_16x16x32_bf16 v[92:95], v[220:223], v[56:59], 0
	v_mfma_f32_16x16x32_bf16 v[96:99], v[220:223], v[64:67], 0
	v_mfma_f32_16x16x32_bf16 v[100:103], v[224:227], v[56:59], 0
	v_mfma_f32_16x16x32_bf16 v[104:107], v[224:227], v[64:67], 0
	v_mfma_f32_16x16x32_bf16 v[108:111], v[228:231], v[56:59], 0
	v_mfma_f32_16x16x32_bf16 v[112:115], v[228:231], v[64:67], 0
	s_waitcnt lgkmcnt(4)
	v_mfma_f32_16x16x32_bf16 v[84:87], v[232:235], v[60:63], v[84:87]
	v_mfma_f32_16x16x32_bf16 v[88:91], v[232:235], v[68:71], v[88:91]
	v_mfma_f32_16x16x32_bf16 v[92:95], v[236:239], v[60:63], v[92:95]
	v_mfma_f32_16x16x32_bf16 v[96:99], v[236:239], v[68:71], v[96:99]
	v_mfma_f32_16x16x32_bf16 v[100:103], v[240:243], v[60:63], v[100:103]
	v_mfma_f32_16x16x32_bf16 v[104:107], v[240:243], v[68:71], v[104:107]
	v_mfma_f32_16x16x32_bf16 v[108:111], v[244:247], v[60:63], v[108:111]
	v_mfma_f32_16x16x32_bf16 v[112:115], v[244:247], v[68:71], v[112:115]
	ds_read_b128 v[216:219], v138 offset:8192
	ds_read_b128 v[220:223], v138 offset:10240
	ds_read_b128 v[224:227], v138 offset:12288
	ds_read_b128 v[228:231], v138 offset:14336
	ds_read_b128 v[232:235], v139
	ds_read_b128 v[236:239], v139 offset:2048
	ds_read_b128 v[240:243], v139 offset:4096
	ds_read_b128 v[244:247], v139 offset:6144
	s_add_i32 s0, s74, 1
	s_lshl_b32 s0, s0, 6
	v_add_u32_e32 v156, s0, v187
	v_cvt_f32_u32_e32 v156, v156
	v_sub_f32_e32 v214, v156, v121
	v_sub_f32_e32 v215, v156, v186
	s_waitcnt lgkmcnt(8)
	v_mfma_f32_16x16x32_bf16 v[72:75], v[164:167], v[140:143], v[72:75]
	v_fma_f32 v84, |v214|, v119, v84
	v_exp_f32_e32 v84, v84
	v_mfma_f32_16x16x32_bf16 v[76:79], v[164:167], v[144:147], v[76:79]
	v_add_f32_e32 v129, v129, v84
	v_add_f32_e32 v81, 1.0, v214
	v_fma_f32 v85, |v81|, v119, v85
	v_exp_f32_e32 v85, v85
	v_mfma_f32_16x16x32_bf16 v[52:55], v[168:171], v[140:143], v[52:55]
	v_add_f32_e32 v129, v129, v85
	v_add_f32_e32 v82, 2.0, v214
	v_fma_f32 v86, |v82|, v119, v86
	v_exp_f32_e32 v86, v86
	v_mfma_f32_16x16x32_bf16 v[48:51], v[168:171], v[144:147], v[48:51]
	v_add_f32_e32 v129, v129, v86
	v_add_f32_e32 v83, 0x40400000, v214
	v_fma_f32 v87, |v83|, v119, v87
	v_exp_f32_e32 v87, v87
	v_mfma_f32_16x16x32_bf16 v[44:47], v[188:191], v[140:143], v[44:47]
	v_add_f32_e32 v129, v129, v87
	v_fma_f32 v88, |v215|, v119, v88
	v_exp_f32_e32 v88, v88
	v_mfma_f32_16x16x32_bf16 v[40:43], v[188:191], v[144:147], v[40:43]
	v_add_f32_e32 v128, v128, v88
	v_add_f32_e32 v81, 1.0, v215
	v_fma_f32 v89, |v81|, v119, v89
	v_exp_f32_e32 v89, v89
	v_mfma_f32_16x16x32_bf16 v[36:39], v[192:195], v[140:143], v[36:39]
	v_add_f32_e32 v128, v128, v89
	v_add_f32_e32 v82, 2.0, v215
	v_fma_f32 v90, |v82|, v119, v90
	v_exp_f32_e32 v90, v90
	v_mfma_f32_16x16x32_bf16 v[32:35], v[192:195], v[144:147], v[32:35]
	v_add_f32_e32 v128, v128, v90
	v_add_f32_e32 v83, 0x40400000, v215
	v_fma_f32 v91, |v83|, v119, v91
	v_exp_f32_e32 v91, v91
	ds_read_b128 v[164:167], v139 offset:8192
	ds_read_b128 v[168:171], v139 offset:10240
	ds_read_b128 v[188:191], v139 offset:12288
	ds_read_b128 v[192:195], v139 offset:14336
	s_waitcnt lgkmcnt(8)
	v_mfma_f32_16x16x32_bf16 v[28:31], v[216:219], v[140:143], v[28:31]
	v_add_f32_e32 v128, v128, v91
	v_add_f32_e32 v80, 0x41800000, v214
	v_fma_f32 v92, |v80|, v119, v92
	v_exp_f32_e32 v92, v92
	v_mfma_f32_16x16x32_bf16 v[20:23], v[216:219], v[144:147], v[20:23]
	v_add_f32_e32 v129, v129, v92
	v_add_f32_e32 v81, 0x41880000, v214
	v_fma_f32 v93, |v81|, v119, v93
	v_exp_f32_e32 v93, v93
	v_mfma_f32_16x16x32_bf16 v[16:19], v[220:223], v[140:143], v[16:19]
	v_add_f32_e32 v129, v129, v93
	v_add_f32_e32 v82, 0x41900000, v214
	v_fma_f32 v94, |v82|, v119, v94
	v_exp_f32_e32 v94, v94
	v_mfma_f32_16x16x32_bf16 v[12:15], v[220:223], v[144:147], v[12:15]
	v_add_f32_e32 v129, v129, v94
	v_add_f32_e32 v83, 0x41980000, v214
	v_fma_f32 v95, |v83|, v119, v95
	v_exp_f32_e32 v95, v95
	v_mfma_f32_16x16x32_bf16 v[24:27], v[224:227], v[140:143], v[24:27]
	v_add_f32_e32 v129, v129, v95
	v_add_f32_e32 v80, 0x41800000, v215
	v_fma_f32 v96, |v80|, v119, v96
	v_exp_f32_e32 v96, v96
	v_mfma_f32_16x16x32_bf16 v[8:11], v[224:227], v[144:147], v[8:11]
	v_add_f32_e32 v128, v128, v96
	v_add_f32_e32 v81, 0x41880000, v215
	v_fma_f32 v97, |v81|, v119, v97
	v_exp_f32_e32 v97, v97
	v_mfma_f32_16x16x32_bf16 v[4:7], v[228:231], v[140:143], v[4:7]
	v_add_f32_e32 v128, v128, v97
	v_add_f32_e32 v82, 0x41900000, v215
	v_fma_f32 v98, |v82|, v119, v98
	v_exp_f32_e32 v98, v98
	v_mfma_f32_16x16x32_bf16 v[0:3], v[228:231], v[144:147], v[0:3]
	v_add_f32_e32 v128, v128, v98
	v_add_f32_e32 v83, 0x41980000, v215
	v_fma_f32 v99, |v83|, v119, v99
	v_exp_f32_e32 v99, v99
	s_waitcnt lgkmcnt(4)
; #define LAS __attribute__((address_space(3)))
; #define LAS __attribute__((address_space(3)))
; DI unsigned pk(float lo, float hi) { return pg8::cvt_pk_bf16(lo, hi); }
; #define MFMA16(a, b, c) __builtin_amdgcn_mfma_f32_16x16x32_bf16((a), (b), (c), 0, 0, 0)
; DI void attn_unit(const bf16_t* z, const bf16_t* VT, bf16_t* Y, const float* subg, ldsp lds, int tid, int b, int h, int qb, float lam, float ns, float oscale, int win) {
;     ...
;             const float dl0 = (float)(64 * j + 4 * fq) - tq0, dl1 = (float)(64 * j + 4 * fq) - tq1;
; #pragma unroll
;             for (int m = 0; m < 2; ++m) {
;                 bf16x8 vf[8];
; #pragma unroll
;                 for (int et = 0; et < 8; ++et) vf[et] = *(LAS bf16x8*)(sb + voff[m] + et * 2048);
;                 bf16x8 pf[2];
; #pragma unroll
;                 for (int qt = 0; qt < 2; ++qt) {
;                     const float dl = qt ? dl1 : dl0;
;                     float p[8];
; #pragma unroll
;                     for (int i = 0; i < 8; ++i) {
;                         const int kt = 2 * m + (i >> 2), r = i & 3;
;                         p[i] = __builtin_amdgcn_exp2f(fmaf(fabsf(dl + (float)(16 * kt + r)), ns, S[kt][qt][r]));
;                     }
;                     const float sum = ((p[0] + p[1]) + (p[2] + p[3])) + ((p[4] + p[5]) + (p[6] + p[7]));
;                     if (qt) ls1 += sum; else ls0 += sum;
;                     u32x4 u; u.x = pk(p[0], p[1]); u.y = pk(p[2], p[3]); u.z = pk(p[4], p[5]); u.w = pk(p[6], p[7]);
;                     pf[qt] = __builtin_bit_cast(bf16x8, u);
;                 }
; #pragma unroll
;                 for (int et = 0; et < 8; ++et)
; #pragma unroll
;                     for (int qt = 0; qt < 2; ++qt) O[et][qt] = MFMA16(vf[et], pf[qt], O[et][qt]);
	v_mfma_f32_16x16x32_bf16 v[72:75], v[232:235], v[148:151], v[72:75]
	v_add_f32_e32 v128, v128, v99
	v_add_f32_e32 v80, 0x42000000, v214
	v_fma_f32 v100, |v80|, v119, v100
	v_exp_f32_e32 v100, v100
	v_mfma_f32_16x16x32_bf16 v[76:79], v[232:235], v[152:155], v[76:79]
	v_add_f32_e32 v129, v129, v100
	v_add_f32_e32 v81, 0x42040000, v214
	v_fma_f32 v101, |v81|, v119, v101
	v_exp_f32_e32 v101, v101
	v_mfma_f32_16x16x32_bf16 v[52:55], v[236:239], v[148:151], v[52:55]
	v_add_f32_e32 v129, v129, v101
	v_add_f32_e32 v82, 0x42080000, v214
	v_fma_f32 v102, |v82|, v119, v102
	v_exp_f32_e32 v102, v102
	v_mfma_f32_16x16x32_bf16 v[48:51], v[236:239], v[152:155], v[48:51]
	v_add_f32_e32 v129, v129, v102
	v_add_f32_e32 v83, 0x420c0000, v214
	v_fma_f32 v103, |v83|, v119, v103
	v_exp_f32_e32 v103, v103
	v_mfma_f32_16x16x32_bf16 v[44:47], v[240:243], v[148:151], v[44:47]
	v_add_f32_e32 v129, v129, v103
	v_add_f32_e32 v80, 0x42000000, v215
	v_fma_f32 v104, |v80|, v119, v104
	v_exp_f32_e32 v104, v104
	v_mfma_f32_16x16x32_bf16 v[40:43], v[240:243], v[152:155], v[40:43]
	v_add_f32_e32 v128, v128, v104
	v_add_f32_e32 v81, 0x42040000, v215
	v_fma_f32 v105, |v81|, v119, v105
	v_exp_f32_e32 v105, v105
	v_mfma_f32_16x16x32_bf16 v[36:39], v[244:247], v[148:151], v[36:39]
	v_add_f32_e32 v128, v128, v105
	v_add_f32_e32 v82, 0x42080000, v215
	v_fma_f32 v106, |v82|, v119, v106
	v_exp_f32_e32 v106, v106
	v_mfma_f32_16x16x32_bf16 v[32:35], v[244:247], v[152:155], v[32:35]
	v_add_f32_e32 v128, v128, v106
	v_add_f32_e32 v83, 0x420c0000, v215
	v_fma_f32 v107, |v83|, v119, v107
	v_exp_f32_e32 v107, v107
	s_waitcnt lgkmcnt(0)
	v_mfma_f32_16x16x32_bf16 v[28:31], v[164:167], v[148:151], v[28:31]
	v_add_f32_e32 v128, v128, v107
	v_add_f32_e32 v80, 0x42400000, v214
	v_fma_f32 v108, |v80|, v119, v108
	v_exp_f32_e32 v108, v108
	v_mfma_f32_16x16x32_bf16 v[20:23], v[164:167], v[152:155], v[20:23]
	v_add_f32_e32 v129, v129, v108
	v_add_f32_e32 v81, 0x42440000, v214
	v_fma_f32 v109, |v81|, v119, v109
	v_exp_f32_e32 v109, v109
	v_mfma_f32_16x16x32_bf16 v[16:19], v[168:171], v[148:151], v[16:19]
	v_add_f32_e32 v129, v129, v109
	v_add_f32_e32 v82, 0x42480000, v214
	v_fma_f32 v110, |v82|, v119, v110
	v_exp_f32_e32 v110, v110
	v_mfma_f32_16x16x32_bf16 v[12:15], v[168:171], v[152:155], v[12:15]
	v_add_f32_e32 v129, v129, v110
	v_add_f32_e32 v83, 0x424c0000, v214
	v_fma_f32 v111, |v83|, v119, v111
	v_exp_f32_e32 v111, v111
	v_mfma_f32_16x16x32_bf16 v[24:27], v[188:191], v[148:151], v[24:27]
	v_add_f32_e32 v129, v129, v111
	v_add_f32_e32 v80, 0x42400000, v215
	v_fma_f32 v112, |v80|, v119, v112
	v_exp_f32_e32 v112, v112
	v_mfma_f32_16x16x32_bf16 v[8:11], v[188:191], v[152:155], v[8:11]
	v_add_f32_e32 v128, v128, v112
	v_add_f32_e32 v81, 0x42440000, v215
	v_fma_f32 v113, |v81|, v119, v113
	v_exp_f32_e32 v113, v113
	v_mfma_f32_16x16x32_bf16 v[4:7], v[192:195], v[148:151], v[4:7]
	v_add_f32_e32 v128, v128, v113
	v_add_f32_e32 v82, 0x42480000, v215
	v_fma_f32 v114, |v82|, v119, v114
	v_exp_f32_e32 v114, v114
	v_mfma_f32_16x16x32_bf16 v[0:3], v[192:195], v[152:155], v[0:3]
	v_add_f32_e32 v128, v128, v114
	v_add_f32_e32 v83, 0x424c0000, v215
	v_fma_f32 v115, |v83|, v119, v115
	v_exp_f32_e32 v115, v115
	s_nop 0
	v_add_f32_e32 v128, v128, v115
	s_branch .Lat_end
.Lat_qk:
	ds_read_b128 v[216:219], v134
	ds_read_b128 v[220:223], v134 offset:4096
	ds_read_b128 v[224:227], v134 offset:8192
	ds_read_b128 v[228:231], v134 offset:12288
	ds_read_b128 v[232:235], v135
	ds_read_b128 v[236:239], v135 offset:4096
	ds_read_b128 v[240:243], v135 offset:8192
	ds_read_b128 v[244:247], v135 offset:12288
	s_add_i32 s0, s74, 2
	s_cmp_lt_i32 s0, s11
	s_cbranch_scc0 .Lat_nok_q
	s_mul_i32 s14, s0, 0x70000
	s_add_i32 s14, s14, 0xa00
	s_mov_b32 s15, 0
	v_lshl_add_u64 v[214:215], v[122:123], 0, s[14:15]
	s_add_i32 s1, s101, 1
	s_cmp_ge_i32 s1, 2
	s_cselect_b32 s0, 2, 0
	s_sub_i32 s1, s1, s0
	s_lshl_b32 s1, s1, 15
	s_add_i32 s1, s1, s10
	s_mov_b32 m0, s1
	s_add_i32 s14, s14, 0x38000
	global_load_lds_dwordx4 v[214:215], off
	v_lshl_add_u64 v[80:81], v[122:123], 0, s[14:15]
	s_add_i32 m0, s1, 0x2000
	s_nop 0
	global_load_lds_dwordx4 v[80:81], off

; #define LAS __attribute__((address_space(3)))
; #define LAS __attribute__((address_space(3)))
; #define MFMA16(a, b, c) __builtin_amdgcn_mfma_f32_16x16x32_bf16((a), (b), (c), 0, 0, 0)
; DI void attn_unit(const bf16_t* z, const bf16_t* VT, bf16_t* Y, const float* subg, ldsp lds, int tid, int b, int h, int qb, float lam, float ns, float oscale, int win) {
;     ...
;             for (int ks = 0; ks < 2; ++ks) {
;                 bf16x8 kf[4];
; #pragma unroll
;                 for (int kt = 0; kt < 4; ++kt) kf[kt] = *(LAS bf16x8*)(sb + koff[ks] + kt * 4096);
; #pragma unroll
;                 for (int kt = 0; kt < 4; ++kt)
; #pragma unroll
;                     for (int qt = 0; qt < 2; ++qt) S[kt][qt] = MFMA16(kf[kt], qf[qt][ks], S[kt][qt]);
;             }
;             const float dl0 = (float)(64 * j + 4 * fq) - tq0, dl1 = (float)(64 * j + 4 * fq) - tq1;
; #pragma unroll
;             for (int m = 0; m < 2; ++m) {
;                 bf16x8 vf[8];
; #pragma unroll
;                 for (int et = 0; et < 8; ++et) vf[et] = *(LAS bf16x8*)(sb + voff[m] + et * 2048);
;                 bf16x8 pf[2];
; #pragma unroll
;                 for (int qt = 0; qt < 2; ++qt) {
;                     const float dl = qt ? dl1 : dl0;
;                     float p[8];
; #pragma unroll
;                     for (int i = 0; i < 8; ++i) {
;                         const int kt = 2 * m + (i >> 2), r = i & 3;
;                         p[i] = __builtin_amdgcn_exp2f(fmaf(fabsf(dl + (float)(16 * kt + r)), ns, S[kt][qt][r]));
;                     }
;                     const float sum = ((p[0] + p[1]) + (p[2] + p[3])) + ((p[4] + p[5]) + (p[6] + p[7]));
;                     if (qt) ls1 += sum; else ls0 += sum;
.Lat_nov_q:
	s_waitcnt lgkmcnt(4)
	v_mfma_f32_16x16x32_bf16 v[84:87], v[216:219], v[56:59], 0
	v_mfma_f32_16x16x32_bf16 v[88:91], v[216:219], v[64:67], 0
	v_mfma_f32_16x16x32_bf16 v[92:95], v[220:223], v[56:59], 0
	v_mfma_f32_16x16x32_bf16 v[96:99], v[220:223], v[64:67], 0
	v_mfma_f32_16x16x32_bf16 v[100:103], v[224:227], v[56:59], 0
	v_mfma_f32_16x16x32_bf16 v[104:107], v[224:227], v[64:67], 0
	v_mfma_f32_16x16x32_bf16 v[108:111], v[228:231], v[56:59], 0
	v_mfma_f32_16x16x32_bf16 v[112:115], v[228:231], v[64:67], 0
	s_waitcnt lgkmcnt(0)
	v_mfma_f32_16x16x32_bf16 v[84:87], v[232:235], v[60:63], v[84:87]
	v_mfma_f32_16x16x32_bf16 v[88:91], v[232:235], v[68:71], v[88:91]
	v_mfma_f32_16x16x32_bf16 v[92:95], v[236:239], v[60:63], v[92:95]
	v_mfma_f32_16x16x32_bf16 v[96:99], v[236:239], v[68:71], v[96:99]
	v_mfma_f32_16x16x32_bf16 v[100:103], v[240:243], v[60:63], v[100:103]
	v_mfma_f32_16x16x32_bf16 v[104:107], v[240:243], v[68:71], v[104:107]
	v_mfma_f32_16x16x32_bf16 v[108:111], v[244:247], v[60:63], v[108:111]
	v_mfma_f32_16x16x32_bf16 v[112:115], v[244:247], v[68:71], v[112:115]
	s_add_i32 s0, s74, 1
	s_lshl_b32 s0, s0, 6
	v_add_u32_e32 v156, s0, v187
	v_cvt_f32_u32_e32 v156, v156
	v_sub_f32_e32 v214, v156, v121
	v_sub_f32_e32 v215, v156, v186
	s_nop 3
	v_fma_f32 v84, |v214|, v119, v84
	v_exp_f32_e32 v84, v84
	v_add_f32_e32 v81, 1.0, v214
	v_add_f32_e32 v129, v129, v84
	v_fma_f32 v85, |v81|, v119, v85
	v_exp_f32_e32 v85, v85
	v_add_f32_e32 v82, 2.0, v214
	v_add_f32_e32 v129, v129, v85
	v_fma_f32 v86, |v82|, v119, v86
	v_exp_f32_e32 v86, v86
	v_add_f32_e32 v83, 0x40400000, v214
	v_add_f32_e32 v129, v129, v86
	v_fma_f32 v87, |v83|, v119, v87
	v_exp_f32_e32 v87, v87
	v_fma_f32 v88, |v215|, v119, v88
	v_add_f32_e32 v129, v129, v87
	v_exp_f32_e32 v88, v88
	v_add_f32_e32 v81, 1.0, v215
	v_add_f32_e32 v128, v128, v88
	v_fma_f32 v89, |v81|, v119, v89
	v_exp_f32_e32 v89, v89
	v_add_f32_e32 v82, 2.0, v215
	v_add_f32_e32 v128, v128, v89
	v_fma_f32 v90, |v82|, v119, v90
	v_exp_f32_e32 v90, v90
	v_add_f32_e32 v83, 0x40400000, v215
	v_add_f32_e32 v128, v128, v90
	v_fma_f32 v91, |v83|, v119, v91
	v_exp_f32_e32 v91, v91
	v_add_f32_e32 v80, 0x41800000, v214
	v_add_f32_e32 v128, v128, v91
	v_fma_f32 v92, |v80|, v119, v92
	v_exp_f32_e32 v92, v92
	v_add_f32_e32 v81, 0x41880000, v214
	v_add_f32_e32 v129, v129, v92
	v_fma_f32 v93, |v81|, v119, v93
	v_exp_f32_e32 v93, v93
	v_add_f32_e32 v82, 0x41900000, v214
	v_add_f32_e32 v129, v129, v93
	v_fma_f32 v94, |v82|, v119, v94
	v_exp_f32_e32 v94, v94
	v_add_f32_e32 v83, 0x41980000, v214
	v_add_f32_e32 v129, v129, v94
	v_fma_f32 v95, |v83|, v119, v95
	v_exp_f32_e32 v95, v95
	v_add_f32_e32 v80, 0x41800000, v215
	v_add_f32_e32 v129, v129, v95
	v_fma_f32 v96, |v80|, v119, v96
	v_exp_f32_e32 v96, v96
	v_add_f32_e32 v81, 0x41880000, v215
	v_add_f32_e32 v128, v128, v96
	v_fma_f32 v97, |v81|, v119, v97
	v_exp_f32_e32 v97, v97
	v_add_f32_e32 v82, 0x41900000, v215
	v_add_f32_e32 v128, v128, v97
	v_fma_f32 v98, |v82|, v119, v98
	v_exp_f32_e32 v98, v98
	v_add_f32_e32 v83, 0x41980000, v215
	v_add_f32_e32 v128, v128, v98
	v_fma_f32 v99, |v83|, v119, v99
	v_exp_f32_e32 v99, v99
	v_add_f32_e32 v80, 0x42000000, v214
	v_add_f32_e32 v128, v128, v99
	v_fma_f32 v100, |v80|, v119, v100
	v_exp_f32_e32 v100, v100
	v_add_f32_e32 v81, 0x42040000, v214
	v_add_f32_e32 v129, v129, v100
	v_fma_f32 v101, |v81|, v119, v101
	v_exp_f32_e32 v101, v101
	v_add_f32_e32 v82, 0x42080000, v214
	v_add_f32_e32 v129, v129, v101
	v_fma_f32 v102, |v82|, v119, v102
	v_exp_f32_e32 v102, v102
	v_add_f32_e32 v83, 0x420c0000, v214
	v_add_f32_e32 v129, v129, v102
	v_fma_f32 v103, |v83|, v119, v103
	v_exp_f32_e32 v103, v103
	v_add_f32_e32 v80, 0x42000000, v215
	v_add_f32_e32 v129, v129, v103
	v_fma_f32 v104, |v80|, v119, v104
	v_exp_f32_e32 v104, v104
	v_add_f32_e32 v81, 0x42040000, v215
	v_add_f32_e32 v128, v128, v104
	v_fma_f32 v105, |v81|, v119, v105
	v_exp_f32_e32 v105, v105
	v_add_f32_e32 v82, 0x42080000, v215
	v_add_f32_e32 v128, v128, v105
	v_fma_f32 v106, |v82|, v119, v106
	v_exp_f32_e32 v106, v106
	v_add_f32_e32 v83, 0x420c0000, v215
	v_add_f32_e32 v128, v128, v106
	v_fma_f32 v107, |v83|, v119, v107
	v_exp_f32_e32 v107, v107
	v_add_f32_e32 v80, 0x42400000, v214
	v_add_f32_e32 v128, v128, v107
	v_fma_f32 v108, |v80|, v119, v108
	v_exp_f32_e32 v108, v108
	v_add_f32_e32 v81, 0x42440000, v214
	v_add_f32_e32 v129, v129, v108
	v_fma_f32 v109, |v81|, v119, v109
	v_exp_f32_e32 v109, v109
	v_add_f32_e32 v82, 0x42480000, v214
	v_add_f32_e32 v129, v129, v109
	v_fma_f32 v110, |v82|, v119, v110
	v_exp_f32_e32 v110, v110
	v_add_f32_e32 v83, 0x424c0000, v214
	v_add_f32_e32 v129, v129, v110
	v_fma_f32 v111, |v83|, v119, v111
	v_exp_f32_e32 v111, v111
	v_add_f32_e32 v80, 0x42400000, v215
	v_add_f32_e32 v129, v129, v111
	v_fma_f32 v112, |v80|, v119, v112
	v_exp_f32_e32 v112, v112
	v_add_f32_e32 v81, 0x42440000, v215
	v_add_f32_e32 v128, v128, v112
	v_fma_f32 v113, |v81|, v119, v113
	v_exp_f32_e32 v113, v113
	v_add_f32_e32 v82, 0x42480000, v215
	v_add_f32_e32 v128, v128, v113
	v_fma_f32 v114, |v82|, v119, v114
	v_exp_f32_e32 v114, v114
	v_add_f32_e32 v83, 0x424c0000, v215
	v_add_f32_e32 v128, v128, v114
	v_fma_f32 v115, |v83|, v119, v115
	v_exp_f32_e32 v115, v115
	s_nop 0
	v_add_f32_e32 v128, v128, v115
	s_branch .Lat_end
.Lat_pv:
	ds_read_b128 v[164:167], v138
	ds_read_b128 v[168:171], v138 offset:2048
	ds_read_b128 v[188:191], v138 offset:4096
	ds_read_b128 v[192:195], v138 offset:6144
	ds_read_b128 v[216:219], v138 offset:8192
	ds_read_b128 v[220:223], v138 offset:10240
	ds_read_b128 v[224:227], v138 offset:12288
	ds_read_b128 v[228:231], v138 offset:14336
	ds_read_b128 v[232:235], v139
	ds_read_b128 v[236:239], v139 offset:2048
	ds_read_b128 v[240:243], v139 offset:4096
	ds_read_b128 v[244:247], v139 offset:6144
	s_add_i32 s0, s74, 2
	s_cmp_lt_i32 s0, s11
	s_cbranch_scc0 .Lat_nok_p
	s_mul_i32 s14, s0, 0x70000
	s_add_i32 s14, s14, 0xa00
	s_mov_b32 s15, 0
	v_lshl_add_u64 v[214:215], v[122:123], 0, s[14:15]
	s_add_i32 s1, s101, 1
	s_cmp_ge_i32 s1, 2
	s_cselect_b32 s0, 2, 0
	s_sub_i32 s1, s1, s0
	s_lshl_b32 s1, s1, 15
	s_add_i32 s1, s1, s10
	s_mov_b32 m0, s1
	s_add_i32 s14, s14, 0x38000
	global_load_lds_dwordx4 v[214:215], off
	v_lshl_add_u64 v[80:81], v[122:123], 0, s[14:15]
	s_add_i32 m0, s1, 0x2000
	s_nop 0
	global_load_lds_dwordx4 v[80:81], off

; #define LAS __attribute__((address_space(3)))
; #define LAS __attribute__((address_space(3)))
; DI unsigned pk(float lo, float hi) { return pg8::cvt_pk_bf16(lo, hi); }
; #define MFMA16(a, b, c) __builtin_amdgcn_mfma_f32_16x16x32_bf16((a), (b), (c), 0, 0, 0)
; DI void attn_unit(const bf16_t* z, const bf16_t* VT, bf16_t* Y, const float* subg, ldsp lds, int tid, int b, int h, int qb, float lam, float ns, float oscale, int win) {
;     ...
;             for (int m = 0; m < 2; ++m) {
;                 bf16x8 vf[8];
; #pragma unroll
;                 for (int et = 0; et < 8; ++et) vf[et] = *(LAS bf16x8*)(sb + voff[m] + et * 2048);
;                 bf16x8 pf[2];
; #pragma unroll
;                 for (int qt = 0; qt < 2; ++qt) {
;                     const float dl = qt ? dl1 : dl0;
;                     float p[8];
; #pragma unroll
;                     for (int i = 0; i < 8; ++i) {
;                         const int kt = 2 * m + (i >> 2), r = i & 3;
;                         p[i] = __builtin_amdgcn_exp2f(fmaf(fabsf(dl + (float)(16 * kt + r)), ns, S[kt][qt][r]));
;                     }
;                     const float sum = ((p[0] + p[1]) + (p[2] + p[3])) + ((p[4] + p[5]) + (p[6] + p[7]));
;                     if (qt) ls1 += sum; else ls0 += sum;
;                     u32x4 u; u.x = pk(p[0], p[1]); u.y = pk(p[2], p[3]); u.z = pk(p[4], p[5]); u.w = pk(p[6], p[7]);
;                     pf[qt] = __builtin_bit_cast(bf16x8, u);
;                 }
; #pragma unroll
;                 for (int et = 0; et < 8; ++et)
; #pragma unroll
;                     for (int qt = 0; qt < 2; ++qt) O[et][qt] = MFMA16(vf[et], pf[qt], O[et][qt]);
;             }
;         }
;         asm volatile("s_waitcnt vmcnt(0)" ::: "memory");
;         __syncthreads();
;     }
.Lat_nov_p:
	v_cvt_pk_bf16_f32 v140, v84, v85
	v_cvt_pk_bf16_f32 v141, v86, v87
	v_cvt_pk_bf16_f32 v142, v92, v93
	v_cvt_pk_bf16_f32 v143, v94, v95
	v_cvt_pk_bf16_f32 v144, v88, v89
	v_cvt_pk_bf16_f32 v145, v90, v91
	v_cvt_pk_bf16_f32 v146, v96, v97
	v_cvt_pk_bf16_f32 v147, v98, v99
	v_cvt_pk_bf16_f32 v148, v100, v101
	v_cvt_pk_bf16_f32 v149, v102, v103
	v_cvt_pk_bf16_f32 v150, v108, v109
	v_cvt_pk_bf16_f32 v151, v110, v111
	v_cvt_pk_bf16_f32 v152, v104, v105
	v_cvt_pk_bf16_f32 v153, v106, v107
	v_cvt_pk_bf16_f32 v154, v112, v113
	v_cvt_pk_bf16_f32 v155, v114, v115
	s_nop 1
	s_waitcnt lgkmcnt(8)
	v_mfma_f32_16x16x32_bf16 v[72:75], v[164:167], v[140:143], v[72:75]
	v_mfma_f32_16x16x32_bf16 v[76:79], v[164:167], v[144:147], v[76:79]
	v_mfma_f32_16x16x32_bf16 v[52:55], v[168:171], v[140:143], v[52:55]
	v_mfma_f32_16x16x32_bf16 v[48:51], v[168:171], v[144:147], v[48:51]
	v_mfma_f32_16x16x32_bf16 v[44:47], v[188:191], v[140:143], v[44:47]
	v_mfma_f32_16x16x32_bf16 v[40:43], v[188:191], v[144:147], v[40:43]
	v_mfma_f32_16x16x32_bf16 v[36:39], v[192:195], v[140:143], v[36:39]
	v_mfma_f32_16x16x32_bf16 v[32:35], v[192:195], v[144:147], v[32:35]
	ds_read_b128 v[164:167], v139 offset:8192
	ds_read_b128 v[168:171], v139 offset:10240
	ds_read_b128 v[188:191], v139 offset:12288
	ds_read_b128 v[192:195], v139 offset:14336
	s_waitcnt lgkmcnt(8)
	v_mfma_f32_16x16x32_bf16 v[28:31], v[216:219], v[140:143], v[28:31]
	v_mfma_f32_16x16x32_bf16 v[20:23], v[216:219], v[144:147], v[20:23]
	v_mfma_f32_16x16x32_bf16 v[16:19], v[220:223], v[140:143], v[16:19]
	v_mfma_f32_16x16x32_bf16 v[12:15], v[220:223], v[144:147], v[12:15]
	v_mfma_f32_16x16x32_bf16 v[24:27], v[224:227], v[140:143], v[24:27]
	v_mfma_f32_16x16x32_bf16 v[8:11], v[224:227], v[144:147], v[8:11]
	v_mfma_f32_16x16x32_bf16 v[4:7], v[228:231], v[140:143], v[4:7]
	v_mfma_f32_16x16x32_bf16 v[0:3], v[228:231], v[144:147], v[0:3]
	s_waitcnt lgkmcnt(4)
	v_mfma_f32_16x16x32_bf16 v[72:75], v[232:235], v[148:151], v[72:75]
	v_mfma_f32_16x16x32_bf16 v[76:79], v[232:235], v[152:155], v[76:79]
	v_mfma_f32_16x16x32_bf16 v[52:55], v[236:239], v[148:151], v[52:55]
	v_mfma_f32_16x16x32_bf16 v[48:51], v[236:239], v[152:155], v[48:51]
	v_mfma_f32_16x16x32_bf16 v[44:47], v[240:243], v[148:151], v[44:47]
	v_mfma_f32_16x16x32_bf16 v[40:43], v[240:243], v[152:155], v[40:43]
	v_mfma_f32_16x16x32_bf16 v[36:39], v[244:247], v[148:151], v[36:39]
	v_mfma_f32_16x16x32_bf16 v[32:35], v[244:247], v[152:155], v[32:35]
	s_waitcnt lgkmcnt(0)
	v_mfma_f32_16x16x32_bf16 v[28:31], v[164:167], v[148:151], v[28:31]
	v_mfma_f32_16x16x32_bf16 v[20:23], v[164:167], v[152:155], v[20:23]
	v_mfma_f32_16x16x32_bf16 v[16:19], v[168:171], v[148:151], v[16:19]
	v_mfma_f32_16x16x32_bf16 v[12:15], v[168:171], v[152:155], v[12:15]
	v_mfma_f32_16x16x32_bf16 v[24:27], v[188:191], v[148:151], v[24:27]
	v_mfma_f32_16x16x32_bf16 v[8:11], v[188:191], v[152:155], v[8:11]
	v_mfma_f32_16x16x32_bf16 v[4:7], v[192:195], v[148:151], v[4:7]
	v_mfma_f32_16x16x32_bf16 v[0:3], v[192:195], v[152:155], v[0:3]
.Lat_end:
	s_waitcnt vmcnt(0)
	s_waitcnt lgkmcnt(0)
	s_barrier
	s_add_i32 s101, s101, 1
	s_cmp_ge_i32 s101, 2
	s_cselect_b32 s0, 2, 0
	s_sub_i32 s101, s101, s0
	s_add_i32 s74, s74, 1
	s_cmp_lt_i32 s74, s11
	s_cbranch_scc1 .Lat_loop
; #define LAS __attribute__((address_space(3)))
; #define LAS __attribute__((address_space(3)))
; DI void attn_unit(const bf16_t* z, const bf16_t* VT, bf16_t* Y, const float* subg, ldsp lds, int tid, int b, int h, int qb, float lam, float ns, float oscale, int win) {
;     ...
;     ls0 += __shfl_xor(ls0, 16); ls0 += __shfl_xor(ls0, 32);
;     ls1 += __shfl_xor(ls1, 16); ls1 += __shfl_xor(ls1, 32);
;     const float sc0 = comp ? lam / ls0 : 1.0f / ls0, sc1 = comp ? lam / ls1 : 1.0f / ls1;
;     const ldsp xp = lds + g * 16384 + lane * 4;
;     if (comp) {
; #pragma unroll
;         for (int e = 0; e < 8; ++e)
; #pragma unroll
;             for (int qt = 0; qt < 2; ++qt)
; #pragma unroll
;                 for (int r = 0; r < 4; ++r) *(LAS float*)(xp + ((2 * e + qt) * 4 + r) * 256) = O[e][qt][r] * (qt ? sc1 : sc0);
;     }
.Lat_exit:
.LBB0_419:
	s_or_b64 exec, exec, s[28:29]
	ds_bpermute_b32 v57, v172, v129
	ds_bpermute_b32 v56, v172, v128
	s_cmp_eq_u32 s9, 0
	s_cselect_b64 s[0:1], -1, 0
	s_lshl_b32 s8, s8, 14
	s_add_i32 s8, s8, 0
	s_waitcnt lgkmcnt(0)
	v_pk_add_f32 v[56:57], v[128:129], v[56:57]
	ds_bpermute_b32 v59, v173, v57
	ds_bpermute_b32 v58, v173, v56
	v_ashrrev_i32_e32 v121, 31, v120
	v_ashrrev_i32_e32 v119, 31, v118
	v_lshl_add_u32 v70, v178, 2, s8
	s_waitcnt lgkmcnt(0)
	v_pk_add_f32 v[56:57], v[56:57], v[58:59]
	v_cndmask_b32_e64 v58, v174, 1.0, s[0:1]
	v_div_scale_f32 v59, s[10:11], v57, v57, v58
	v_rcp_f32_e32 v60, v59
	s_nop 0
	v_fma_f32 v61, -v59, v60, 1.0
	v_fmac_f32_e32 v60, v61, v60
	v_div_scale_f32 v61, vcc, v58, v57, v58
	v_mul_f32_e32 v62, v61, v60
	v_fma_f32 v63, -v59, v62, v61
	v_fmac_f32_e32 v62, v63, v60
	v_fma_f32 v59, -v59, v62, v61
	v_div_fmas_f32 v59, v59, v60, v62
	v_div_fixup_f32 v57, v59, v57, v58
	v_div_scale_f32 v59, s[10:11], v56, v56, v58
	v_rcp_f32_e32 v60, v59
	s_nop 0
	v_fma_f32 v61, -v59, v60, 1.0
	v_fmac_f32_e32 v60, v61, v60
	v_div_scale_f32 v61, vcc, v58, v56, v58
	v_mul_f32_e32 v62, v61, v60
	v_fma_f32 v63, -v59, v62, v61
	v_fmac_f32_e32 v62, v63, v60
	v_fma_f32 v59, -v59, v62, v61
	v_div_fmas_f32 v59, v59, v60, v62
	v_div_fixup_f32 v56, v59, v56, v58
	s_and_b64 vcc, exec, s[0:1]
	s_cbranch_vccnz .LBB0_421
	v_mul_f32_e32 v58, v72, v57
	v_mul_f32_e32 v59, v73, v57
	ds_write2st64_b32 v70, v58, v59 offset1:1
	v_mul_f32_e32 v58, v74, v57
	v_mul_f32_e32 v59, v75, v57
	ds_write2st64_b32 v70, v58, v59 offset0:2 offset1:3
	v_mul_f32_e32 v58, v76, v56
	v_mul_f32_e32 v59, v77, v56
	ds_write2st64_b32 v70, v58, v59 offset0:4 offset1:5
	v_mul_f32_e32 v58, v78, v56
	v_mul_f32_e32 v59, v79, v56
	ds_write2st64_b32 v70, v58, v59 offset0:6 offset1:7
	v_mul_f32_e32 v58, v52, v57
	v_mul_f32_e32 v59, v53, v57
	ds_write2st64_b32 v70, v58, v59 offset0:8 offset1:9
	v_mul_f32_e32 v58, v54, v57
	v_mul_f32_e32 v59, v55, v57
	ds_write2st64_b32 v70, v58, v59 offset0:10 offset1:11
	v_mul_f32_e32 v58, v48, v56
	v_mul_f32_e32 v59, v49, v56
	ds_write2st64_b32 v70, v58, v59 offset0:12 offset1:13
	v_mul_f32_e32 v58, v50, v56
	v_mul_f32_e32 v59, v51, v56
	ds_write2st64_b32 v70, v58, v59 offset0:14 offset1:15
	v_mul_f32_e32 v58, v44, v57
	v_mul_f32_e32 v59, v45, v57
	ds_write2st64_b32 v70, v58, v59 offset0:16 offset1:17
	v_mul_f32_e32 v58, v46, v57
	v_mul_f32_e32 v59, v47, v57
	ds_write2st64_b32 v70, v58, v59 offset0:18 offset1:19
	v_mul_f32_e32 v58, v40, v56
	v_mul_f32_e32 v59, v41, v56
	ds_write2st64_b32 v70, v58, v59 offset0:20 offset1:21
	v_mul_f32_e32 v58, v42, v56
	v_mul_f32_e32 v59, v43, v56
	ds_write2st64_b32 v70, v58, v59 offset0:22 offset1:23
	v_mul_f32_e32 v58, v36, v57
	v_mul_f32_e32 v59, v37, v57
	ds_write2st64_b32 v70, v58, v59 offset0:24 offset1:25
	v_mul_f32_e32 v58, v38, v57
	v_mul_f32_e32 v59, v39, v57
	ds_write2st64_b32 v70, v58, v59 offset0:26 offset1:27
	v_mul_f32_e32 v58, v32, v56
	v_mul_f32_e32 v59, v33, v56
	ds_write2st64_b32 v70, v58, v59 offset0:28 offset1:29
	v_mul_f32_e32 v58, v34, v56
	v_mul_f32_e32 v59, v35, v56
	ds_write2st64_b32 v70, v58, v59 offset0:30 offset1:31
	v_mul_f32_e32 v58, v28, v57
	v_mul_f32_e32 v59, v29, v57
	ds_write2st64_b32 v70, v58, v59 offset0:32 offset1:33
	v_mul_f32_e32 v58, v30, v57
	v_mul_f32_e32 v59, v31, v57
	ds_write2st64_b32 v70, v58, v59 offset0:34 offset1:35
	v_mul_f32_e32 v58, v20, v56
	v_mul_f32_e32 v59, v21, v56
	ds_write2st64_b32 v70, v58, v59 offset0:36 offset1:37
	v_mul_f32_e32 v58, v22, v56
	v_mul_f32_e32 v59, v23, v56
	ds_write2st64_b32 v70, v58, v59 offset0:38 offset1:39
	v_mul_f32_e32 v58, v16, v57
	v_mul_f32_e32 v59, v17, v57
	ds_write2st64_b32 v70, v58, v59 offset0:40 offset1:41
	v_mul_f32_e32 v58, v18, v57
	v_mul_f32_e32 v59, v19, v57
	ds_write2st64_b32 v70, v58, v59 offset0:42 offset1:43
	v_mul_f32_e32 v58, v12, v56
	v_mul_f32_e32 v59, v13, v56
	ds_write2st64_b32 v70, v58, v59 offset0:44 offset1:45
	v_mul_f32_e32 v58, v14, v56
	v_mul_f32_e32 v59, v15, v56
	ds_write2st64_b32 v70, v58, v59 offset0:46 offset1:47
	v_mul_f32_e32 v58, v24, v57
	v_mul_f32_e32 v59, v25, v57
	ds_write2st64_b32 v70, v58, v59 offset0:48 offset1:49
	v_mul_f32_e32 v58, v26, v57
	v_mul_f32_e32 v59, v27, v57
	ds_write2st64_b32 v70, v58, v59 offset0:50 offset1:51
	v_mul_f32_e32 v58, v8, v56
	v_mul_f32_e32 v59, v9, v56
	ds_write2st64_b32 v70, v58, v59 offset0:52 offset1:53
	v_mul_f32_e32 v58, v10, v56
	v_mul_f32_e32 v59, v11, v56
	ds_write2st64_b32 v70, v58, v59 offset0:54 offset1:55
	v_mul_f32_e32 v58, v4, v57
	v_mul_f32_e32 v59, v5, v57
	ds_write2st64_b32 v70, v58, v59 offset0:56 offset1:57
	v_mul_f32_e32 v58, v6, v57
	v_mul_f32_e32 v59, v7, v57
	ds_write2st64_b32 v70, v58, v59 offset0:58 offset1:59
	v_mul_f32_e32 v58, v0, v56
	v_mul_f32_e32 v59, v1, v56
	ds_write2st64_b32 v70, v58, v59 offset0:60 offset1:61
	v_mul_f32_e32 v58, v2, v56
	v_mul_f32_e32 v59, v3, v56
	ds_write2st64_b32 v70, v58, v59 offset0:62 offset1:63

; DI unsigned pk(float lo, float hi) { return pg8::cvt_pk_bf16(lo, hi); }
;     DI void operator()(const f32x4 (&acc)[2][2][4][2], const pg8::Unit& u, int wr, int wc, int fr, int fq) const {
;     ...
;                 const int row = row0 + ai * 128 + m * 16;
;                 const f32x4 p = pp[ai * 4 + m];
;                 float s = (p[0] + p[1]) + (p[2] + p[3]);
;                 s += __shfl_xor(s, 16); s += __shfl_xor(s, 32);
;                 const float rstd = rsqrtf(s * (1.0f / D) + EPS);
;                 bf16_t* rowp = O + (size_t)row * ldc + col0;
; #pragma unroll
;                 for (int bj = 0; bj < 2; ++bj) {
;                     f32x4 v0 = acc[ai][bj][m][0] * rstd, v1 = acc[ai][bj][m][1] * rstd;
;                     if (act) {
; #pragma unroll
;                         for (int k = 0; k < 4; ++k) { float a = fmaxf(v0[k], 0.f), b = fmaxf(v1[k], 0.f); v0[k] = a * a; v1[k] = b * b; }
;                     }
;                     u32x4 w; w.x = pk(v0[0], v0[1]); w.y = pk(v0[2], v0[3]); w.z = pk(v1[0], v1[1]); w.w = pk(v1[2], v1[3]);
;                     *(u32x4*)(rowp + bj * 128) = w;
;                 }
.LBB0_472:
	v_lshl_or_b32 v140, s42, 8, v216
	v_mad_i64_i32 v[190:191], s[44:45], v190, s9, 0
	v_mov_b32_e32 v193, v192
	v_ashrrev_i32_e32 v141, 31, v140
	v_lshl_add_u64 v[190:191], v[190:191], 1, s[70:71]
	v_cvt_pk_bf16_f32 v144, v144, v145
	v_cvt_pk_bf16_f32 v145, v146, v147
	v_cvt_pk_bf16_f32 v146, v194, v195
	v_cvt_pk_bf16_f32 v147, v142, v143
	v_mov_b32_e32 v142, v192
	v_mov_b32_e32 v143, v192
	v_lshl_add_u64 v[190:191], v[140:141], 1, v[190:191]
	v_pk_mul_f32 v[134:135], v[134:135], v[142:143]
	v_pk_mul_f32 v[132:133], v[132:133], v[192:193]
	v_pk_mul_f32 v[130:131], v[130:131], v[142:143]
	s_and_b64 vcc, exec, s[38:39]
	v_pk_mul_f32 v[128:129], v[128:129], v[192:193]
	global_store_dwordx4 v[190:191], v[144:147], off nt
	s_cbranch_vccnz .LBB0_474
	v_max_f32_e32 v132, v132, v132
	v_max_f32_e32 v128, v128, v128
	v_max_f32_e32 v133, v133, v133
	v_max_f32_e32 v129, v129, v129
	v_max_f32_e32 v134, v134, v134
	v_max_f32_e32 v130, v130, v130
	v_max_f32_e32 v135, v135, v135
	v_max_f32_e32 v131, v131, v131
	v_max_f32_e32 v132, 0, v132
	v_max_f32_e32 v128, 0, v128
	v_max_f32_e32 v133, 0, v133
	v_max_f32_e32 v129, 0, v129
	v_max_f32_e32 v134, 0, v134
	v_max_f32_e32 v130, 0, v130
	v_max_f32_e32 v135, 0, v135
	v_max_f32_e32 v131, 0, v131
	v_pk_mul_f32 v[132:133], v[132:133], v[132:133]
	v_pk_mul_f32 v[134:135], v[134:135], v[134:135]
	v_pk_mul_f32 v[128:129], v[128:129], v[128:129]
	v_pk_mul_f32 v[130:131], v[130:131], v[130:131]
.LBB0_474:
	v_cvt_pk_bf16_f32 v132, v132, v133
	v_cvt_pk_bf16_f32 v133, v134, v135
	v_cvt_pk_bf16_f32 v134, v128, v129
	v_mov_b32_e32 v128, v153
	v_mov_b32_e32 v129, v154
	v_mov_b32_e32 v153, v155
	v_pk_add_f32 v[128:129], v[128:129], v[152:153]
	v_cvt_pk_bf16_f32 v135, v130, v131
	global_store_dwordx4 v[190:191], v[132:135], off offset:256 nt
	v_add_f32_e32 v128, v128, v129
	ds_bpermute_b32 v129, v177, v128
	s_waitcnt lgkmcnt(0)
	v_add_f32_e32 v128, v128, v129
	ds_bpermute_b32 v129, v179, v128
	s_waitcnt lgkmcnt(0)
	v_add_f32_e32 v128, v128, v129
	v_fmamk_f32 v128, v128, 0x3a800000, v162
	v_cmp_gt_f32_e32 vcc, s47, v128
	v_mul_f32_e32 v129, 0x4b800000, v128
	s_nop 0
	v_cndmask_b32_e32 v128, v128, v129, vcc
	v_rsq_f32_e32 v128, v128
	s_nop 0
	v_mul_f32_e32 v129, 0x45800000, v128
	v_cndmask_b32_e32 v128, v128, v129, vcc
	v_pk_mul_f32 v[126:127], v[126:127], v[128:129] op_sel_hi:[1,0]
	v_pk_mul_f32 v[124:125], v[124:125], v[128:129] op_sel_hi:[1,0]
	v_pk_mul_f32 v[122:123], v[122:123], v[128:129] op_sel_hi:[1,0]
	v_pk_mul_f32 v[120:121], v[120:121], v[128:129] op_sel_hi:[1,0]
	s_and_b64 vcc, exec, s[38:39]
	s_cbranch_vccnz .LBB0_476
	v_max_f32_e32 v124, v124, v124
	v_max_f32_e32 v120, v120, v120
	v_max_f32_e32 v125, v125, v125
	v_max_f32_e32 v121, v121, v121
	v_max_f32_e32 v126, v126, v126
	v_max_f32_e32 v122, v122, v122
	v_max_f32_e32 v127, v127, v127
	v_max_f32_e32 v123, v123, v123
	v_max_f32_e32 v124, 0, v124
	v_max_f32_e32 v120, 0, v120
	v_max_f32_e32 v125, 0, v125
	v_max_f32_e32 v121, 0, v121
	v_max_f32_e32 v126, 0, v126
	v_max_f32_e32 v122, 0, v122
	v_max_f32_e32 v127, 0, v127
	v_max_f32_e32 v123, 0, v123
	v_pk_mul_f32 v[124:125], v[124:125], v[124:125]
	v_pk_mul_f32 v[126:127], v[126:127], v[126:127]
	v_pk_mul_f32 v[120:121], v[120:121], v[120:121]
	v_pk_mul_f32 v[122:123], v[122:123], v[122:123]
.LBB0_476:
	v_mad_i64_i32 v[130:131], s[44:45], v188, s9, 0
	v_mov_b32_e32 v129, v128
	v_lshl_add_u64 v[130:131], v[130:131], 1, s[70:71]
	v_cvt_pk_bf16_f32 v124, v124, v125
	v_cvt_pk_bf16_f32 v125, v126, v127
	v_cvt_pk_bf16_f32 v126, v120, v121
	v_mov_b32_e32 v120, v128
	v_mov_b32_e32 v121, v128
	v_lshl_add_u64 v[130:131], v[140:141], 1, v[130:131]
	v_pk_mul_f32 v[114:115], v[114:115], v[120:121]
	v_pk_mul_f32 v[112:113], v[112:113], v[128:129]
	v_pk_mul_f32 v[110:111], v[110:111], v[120:121]
	s_and_b64 vcc, exec, s[38:39]
	v_pk_mul_f32 v[108:109], v[108:109], v[128:129]
	v_cvt_pk_bf16_f32 v127, v122, v123
	global_store_dwordx4 v[130:131], v[124:127], off nt
	s_cbranch_vccnz .LBB0_478
	v_max_f32_e32 v112, v112, v112
	v_max_f32_e32 v108, v108, v108
	v_max_f32_e32 v113, v113, v113
	v_max_f32_e32 v109, v109, v109
	v_max_f32_e32 v114, v114, v114
	v_max_f32_e32 v110, v110, v110
	v_max_f32_e32 v115, v115, v115
	v_max_f32_e32 v111, v111, v111
	v_max_f32_e32 v112, 0, v112
	v_max_f32_e32 v108, 0, v108
	v_max_f32_e32 v113, 0, v113
	v_max_f32_e32 v109, 0, v109
	v_max_f32_e32 v114, 0, v114
	v_max_f32_e32 v110, 0, v110
	v_max_f32_e32 v115, 0, v115
	v_max_f32_e32 v111, 0, v111
	v_pk_mul_f32 v[112:113], v[112:113], v[112:113]
	v_pk_mul_f32 v[114:115], v[114:115], v[114:115]
	v_pk_mul_f32 v[108:109], v[108:109], v[108:109]
	v_pk_mul_f32 v[110:111], v[110:111], v[110:111]
.LBB0_478:
	v_cvt_pk_bf16_f32 v112, v112, v113
	v_cvt_pk_bf16_f32 v113, v114, v115
	v_cvt_pk_bf16_f32 v114, v108, v109
	v_mov_b32_e32 v108, v149
	v_mov_b32_e32 v109, v150
	v_mov_b32_e32 v149, v151
	v_pk_add_f32 v[108:109], v[108:109], v[148:149]
	v_cvt_pk_bf16_f32 v115, v110, v111
	global_store_dwordx4 v[130:131], v[112:115], off offset:256 nt
	v_add_f32_e32 v108, v108, v109
	ds_bpermute_b32 v109, v177, v108
	s_waitcnt lgkmcnt(0)
	v_add_f32_e32 v108, v108, v109
	ds_bpermute_b32 v109, v179, v108
	s_waitcnt lgkmcnt(0)
	v_add_f32_e32 v108, v108, v109
	v_fmamk_f32 v108, v108, 0x3a800000, v162
	v_cmp_gt_f32_e32 vcc, s47, v108
	v_mul_f32_e32 v109, 0x4b800000, v108
	s_nop 0
	v_cndmask_b32_e32 v108, v108, v109, vcc
	v_rsq_f32_e32 v108, v108
	s_nop 0
	v_mul_f32_e32 v109, 0x45800000, v108
	v_cndmask_b32_e32 v108, v108, v109, vcc
	v_pk_mul_f32 v[106:107], v[106:107], v[108:109] op_sel_hi:[1,0]
	v_pk_mul_f32 v[104:105], v[104:105], v[108:109] op_sel_hi:[1,0]
	v_pk_mul_f32 v[102:103], v[102:103], v[108:109] op_sel_hi:[1,0]
	v_pk_mul_f32 v[100:101], v[100:101], v[108:109] op_sel_hi:[1,0]
	s_and_b64 vcc, exec, s[38:39]
	s_cbranch_vccnz .LBB0_480
	v_max_f32_e32 v104, v104, v104
	v_max_f32_e32 v100, v100, v100
	v_max_f32_e32 v105, v105, v105
	v_max_f32_e32 v101, v101, v101
	v_max_f32_e32 v106, v106, v106
	v_max_f32_e32 v102, v102, v102
	v_max_f32_e32 v107, v107, v107
	v_max_f32_e32 v103, v103, v103
	v_max_f32_e32 v104, 0, v104
	v_max_f32_e32 v100, 0, v100
	v_max_f32_e32 v105, 0, v105
	v_max_f32_e32 v101, 0, v101
	v_max_f32_e32 v106, 0, v106
	v_max_f32_e32 v102, 0, v102
	v_max_f32_e32 v107, 0, v107
	v_max_f32_e32 v103, 0, v103
	v_pk_mul_f32 v[104:105], v[104:105], v[104:105]
	v_pk_mul_f32 v[106:107], v[106:107], v[106:107]
	v_pk_mul_f32 v[100:101], v[100:101], v[100:101]
	v_pk_mul_f32 v[102:103], v[102:103], v[102:103]
; DI unsigned pk(float lo, float hi) { return pg8::cvt_pk_bf16(lo, hi); }
;     DI void operator()(const f32x4 (&acc)[2][2][4][2], const pg8::Unit& u, int wr, int wc, int fr, int fq) const {
;     ...
;                 const int row = row0 + ai * 128 + m * 16;
;                 const f32x4 p = pp[ai * 4 + m];
;                 float s = (p[0] + p[1]) + (p[2] + p[3]);
;                 s += __shfl_xor(s, 16); s += __shfl_xor(s, 32);
;                 const float rstd = rsqrtf(s * (1.0f / D) + EPS);
;                 bf16_t* rowp = O + (size_t)row * ldc + col0;
; #pragma unroll
;                 for (int bj = 0; bj < 2; ++bj) {
;                     f32x4 v0 = acc[ai][bj][m][0] * rstd, v1 = acc[ai][bj][m][1] * rstd;
;                     if (act) {
; #pragma unroll
;                         for (int k = 0; k < 4; ++k) { float a = fmaxf(v0[k], 0.f), b = fmaxf(v1[k], 0.f); v0[k] = a * a; v1[k] = b * b; }
;                     }
;                     u32x4 w; w.x = pk(v0[0], v0[1]); w.y = pk(v0[2], v0[3]); w.z = pk(v1[0], v1[1]); w.w = pk(v1[2], v1[3]);
;                     *(u32x4*)(rowp + bj * 128) = w;
;                 }
.LBB0_480:
	v_mad_i64_i32 v[110:111], s[44:45], v186, s9, 0
	v_mov_b32_e32 v109, v108
	v_lshl_add_u64 v[110:111], v[110:111], 1, s[70:71]
	v_cvt_pk_bf16_f32 v104, v104, v105
	v_cvt_pk_bf16_f32 v105, v106, v107
	v_cvt_pk_bf16_f32 v106, v100, v101
	v_mov_b32_e32 v100, v108
	v_mov_b32_e32 v101, v108
	v_lshl_add_u64 v[110:111], v[140:141], 1, v[110:111]
	v_pk_mul_f32 v[94:95], v[94:95], v[100:101]
	v_pk_mul_f32 v[92:93], v[92:93], v[108:109]
	v_pk_mul_f32 v[90:91], v[90:91], v[100:101]
	s_and_b64 vcc, exec, s[38:39]
	v_pk_mul_f32 v[88:89], v[88:89], v[108:109]
	v_cvt_pk_bf16_f32 v107, v102, v103
	global_store_dwordx4 v[110:111], v[104:107], off nt
	s_cbranch_vccnz .LBB0_482
	v_max_f32_e32 v92, v92, v92
	v_max_f32_e32 v88, v88, v88
	v_max_f32_e32 v93, v93, v93
	v_max_f32_e32 v89, v89, v89
	v_max_f32_e32 v94, v94, v94
	v_max_f32_e32 v90, v90, v90
	v_max_f32_e32 v95, v95, v95
	v_max_f32_e32 v91, v91, v91
	v_max_f32_e32 v92, 0, v92
	v_max_f32_e32 v88, 0, v88
	v_max_f32_e32 v93, 0, v93
	v_max_f32_e32 v89, 0, v89
	v_max_f32_e32 v94, 0, v94
	v_max_f32_e32 v90, 0, v90
	v_max_f32_e32 v95, 0, v95
	v_max_f32_e32 v91, 0, v91
	v_pk_mul_f32 v[92:93], v[92:93], v[92:93]
	v_pk_mul_f32 v[94:95], v[94:95], v[94:95]
	v_pk_mul_f32 v[88:89], v[88:89], v[88:89]
	v_pk_mul_f32 v[90:91], v[90:91], v[90:91]
.LBB0_482:
	v_cvt_pk_bf16_f32 v92, v92, v93
	v_cvt_pk_bf16_f32 v93, v94, v95
	v_cvt_pk_bf16_f32 v94, v88, v89
	v_mov_b32_e32 v88, v137
	v_mov_b32_e32 v89, v138
	v_mov_b32_e32 v137, v139
	v_pk_add_f32 v[88:89], v[88:89], v[136:137]
	v_cvt_pk_bf16_f32 v95, v90, v91
	global_store_dwordx4 v[110:111], v[92:95], off offset:256 nt
	v_add_f32_e32 v88, v88, v89
	ds_bpermute_b32 v89, v177, v88
	s_waitcnt lgkmcnt(0)
	v_add_f32_e32 v88, v88, v89
	ds_bpermute_b32 v89, v179, v88
	s_waitcnt lgkmcnt(0)
	v_add_f32_e32 v88, v88, v89
	v_fmamk_f32 v88, v88, 0x3a800000, v162
	v_cmp_gt_f32_e32 vcc, s47, v88
	v_mul_f32_e32 v89, 0x4b800000, v88
	s_nop 0
	v_cndmask_b32_e32 v88, v88, v89, vcc
	v_rsq_f32_e32 v88, v88
	s_nop 0
	v_mul_f32_e32 v89, 0x45800000, v88
	v_cndmask_b32_e32 v88, v88, v89, vcc
	v_pk_mul_f32 v[86:87], v[86:87], v[88:89] op_sel_hi:[1,0]
	v_pk_mul_f32 v[84:85], v[84:85], v[88:89] op_sel_hi:[1,0]
	v_pk_mul_f32 v[82:83], v[82:83], v[88:89] op_sel_hi:[1,0]
	v_pk_mul_f32 v[80:81], v[80:81], v[88:89] op_sel_hi:[1,0]
	s_and_b64 vcc, exec, s[38:39]
	s_cbranch_vccnz .LBB0_484
	v_max_f32_e32 v84, v84, v84
	v_max_f32_e32 v80, v80, v80
	v_max_f32_e32 v85, v85, v85
	v_max_f32_e32 v81, v81, v81
	v_max_f32_e32 v86, v86, v86
	v_max_f32_e32 v82, v82, v82
	v_max_f32_e32 v87, v87, v87
	v_max_f32_e32 v83, v83, v83
	v_max_f32_e32 v84, 0, v84
	v_max_f32_e32 v80, 0, v80
	v_max_f32_e32 v85, 0, v85
	v_max_f32_e32 v81, 0, v81
	v_max_f32_e32 v86, 0, v86
	v_max_f32_e32 v82, 0, v82
	v_max_f32_e32 v87, 0, v87
	v_max_f32_e32 v83, 0, v83
	v_pk_mul_f32 v[84:85], v[84:85], v[84:85]
	v_pk_mul_f32 v[86:87], v[86:87], v[86:87]
	v_pk_mul_f32 v[80:81], v[80:81], v[80:81]
	v_pk_mul_f32 v[82:83], v[82:83], v[82:83]
.LBB0_484:
	v_mad_i64_i32 v[90:91], s[44:45], v184, s9, 0
	v_mov_b32_e32 v89, v88
	v_lshl_add_u64 v[90:91], v[90:91], 1, s[70:71]
	v_cvt_pk_bf16_f32 v84, v84, v85
	v_cvt_pk_bf16_f32 v85, v86, v87
	v_cvt_pk_bf16_f32 v86, v80, v81
	v_mov_b32_e32 v80, v88
	v_mov_b32_e32 v81, v88
	v_lshl_add_u64 v[90:91], v[140:141], 1, v[90:91]
	v_pk_mul_f32 v[74:75], v[74:75], v[80:81]
	v_pk_mul_f32 v[72:73], v[72:73], v[88:89]
	v_pk_mul_f32 v[70:71], v[70:71], v[80:81]
	s_and_b64 vcc, exec, s[38:39]
	v_pk_mul_f32 v[68:69], v[68:69], v[88:89]
	v_cvt_pk_bf16_f32 v87, v82, v83
	global_store_dwordx4 v[90:91], v[84:87], off nt
	s_cbranch_vccnz .LBB0_486
	v_max_f32_e32 v72, v72, v72
	v_max_f32_e32 v68, v68, v68
	v_max_f32_e32 v73, v73, v73
	v_max_f32_e32 v69, v69, v69
	v_max_f32_e32 v74, v74, v74
	v_max_f32_e32 v70, v70, v70
	v_max_f32_e32 v75, v75, v75
	v_max_f32_e32 v71, v71, v71
	v_max_f32_e32 v72, 0, v72
	v_max_f32_e32 v68, 0, v68
	v_max_f32_e32 v73, 0, v73
	v_max_f32_e32 v69, 0, v69
	v_max_f32_e32 v74, 0, v74
	v_max_f32_e32 v70, 0, v70
	v_max_f32_e32 v75, 0, v75
	v_max_f32_e32 v71, 0, v71
	v_pk_mul_f32 v[72:73], v[72:73], v[72:73]
	v_pk_mul_f32 v[74:75], v[74:75], v[74:75]
	v_pk_mul_f32 v[68:69], v[68:69], v[68:69]
	v_pk_mul_f32 v[70:71], v[70:71], v[70:71]
.LBB0_486:
	v_cvt_pk_bf16_f32 v72, v72, v73
	v_cvt_pk_bf16_f32 v73, v74, v75
	v_cvt_pk_bf16_f32 v74, v68, v69
	v_mov_b32_e32 v68, v117
	v_mov_b32_e32 v69, v118
	v_mov_b32_e32 v117, v119
	v_pk_add_f32 v[68:69], v[68:69], v[116:117]
	v_cvt_pk_bf16_f32 v75, v70, v71
	global_store_dwordx4 v[90:91], v[72:75], off offset:256 nt
	v_add_f32_e32 v68, v68, v69
	ds_bpermute_b32 v69, v177, v68
	s_waitcnt lgkmcnt(0)
	v_add_f32_e32 v68, v68, v69
	ds_bpermute_b32 v69, v179, v68
	s_waitcnt lgkmcnt(0)
	v_add_f32_e32 v68, v68, v69
	v_fmamk_f32 v68, v68, 0x3a800000, v162
	v_cmp_gt_f32_e32 vcc, s47, v68
	v_mul_f32_e32 v69, 0x4b800000, v68
	s_nop 0
	v_cndmask_b32_e32 v68, v68, v69, vcc
	v_rsq_f32_e32 v68, v68
	s_nop 0
	v_mul_f32_e32 v69, 0x45800000, v68
	v_cndmask_b32_e32 v68, v68, v69, vcc
	v_pk_mul_f32 v[66:67], v[66:67], v[68:69] op_sel_hi:[1,0]
	v_pk_mul_f32 v[64:65], v[64:65], v[68:69] op_sel_hi:[1,0]
	v_pk_mul_f32 v[62:63], v[62:63], v[68:69] op_sel_hi:[1,0]
	v_pk_mul_f32 v[60:61], v[60:61], v[68:69] op_sel_hi:[1,0]
	s_and_b64 vcc, exec, s[38:39]
	s_cbranch_vccnz .LBB0_488
	v_max_f32_e32 v64, v64, v64
	v_max_f32_e32 v60, v60, v60
	v_max_f32_e32 v65, v65, v65
	v_max_f32_e32 v61, v61, v61
	v_max_f32_e32 v66, v66, v66
	v_max_f32_e32 v62, v62, v62
	v_max_f32_e32 v67, v67, v67
	v_max_f32_e32 v63, v63, v63
	v_max_f32_e32 v64, 0, v64
	v_max_f32_e32 v60, 0, v60
	v_max_f32_e32 v65, 0, v65
	v_max_f32_e32 v61, 0, v61
	v_max_f32_e32 v66, 0, v66
	v_max_f32_e32 v62, 0, v62
	v_max_f32_e32 v67, 0, v67
	v_max_f32_e32 v63, 0, v63
	v_pk_mul_f32 v[64:65], v[64:65], v[64:65]
	v_pk_mul_f32 v[66:67], v[66:67], v[66:67]
	v_pk_mul_f32 v[60:61], v[60:61], v[60:61]
	v_pk_mul_f32 v[62:63], v[62:63], v[62:63]
; DI unsigned pk(float lo, float hi) { return pg8::cvt_pk_bf16(lo, hi); }
;     DI void operator()(const f32x4 (&acc)[2][2][4][2], const pg8::Unit& u, int wr, int wc, int fr, int fq) const {
;     ...
;                 const int row = row0 + ai * 128 + m * 16;
;                 const f32x4 p = pp[ai * 4 + m];
;                 float s = (p[0] + p[1]) + (p[2] + p[3]);
;                 s += __shfl_xor(s, 16); s += __shfl_xor(s, 32);
;                 const float rstd = rsqrtf(s * (1.0f / D) + EPS);
;                 bf16_t* rowp = O + (size_t)row * ldc + col0;
; #pragma unroll
;                 for (int bj = 0; bj < 2; ++bj) {
;                     f32x4 v0 = acc[ai][bj][m][0] * rstd, v1 = acc[ai][bj][m][1] * rstd;
;                     if (act) {
; #pragma unroll
;                         for (int k = 0; k < 4; ++k) { float a = fmaxf(v0[k], 0.f), b = fmaxf(v1[k], 0.f); v0[k] = a * a; v1[k] = b * b; }
;                     }
;                     u32x4 w; w.x = pk(v0[0], v0[1]); w.y = pk(v0[2], v0[3]); w.z = pk(v1[0], v1[1]); w.w = pk(v1[2], v1[3]);
;                     *(u32x4*)(rowp + bj * 128) = w;
;                 }
.LBB0_488:
	v_mad_i64_i32 v[70:71], s[44:45], v182, s9, 0
	v_mov_b32_e32 v69, v68
	v_lshl_add_u64 v[70:71], v[70:71], 1, s[70:71]
	v_cvt_pk_bf16_f32 v64, v64, v65
	v_cvt_pk_bf16_f32 v65, v66, v67
	v_cvt_pk_bf16_f32 v66, v60, v61
	v_mov_b32_e32 v60, v68
	v_mov_b32_e32 v61, v68
	v_lshl_add_u64 v[70:71], v[140:141], 1, v[70:71]
	v_pk_mul_f32 v[54:55], v[54:55], v[60:61]
	v_pk_mul_f32 v[52:53], v[52:53], v[68:69]
	v_pk_mul_f32 v[50:51], v[50:51], v[60:61]
	s_and_b64 vcc, exec, s[38:39]
	v_pk_mul_f32 v[48:49], v[48:49], v[68:69]
	v_cvt_pk_bf16_f32 v67, v62, v63
	global_store_dwordx4 v[70:71], v[64:67], off nt
	s_cbranch_vccnz .LBB0_490
	v_max_f32_e32 v52, v52, v52
	v_max_f32_e32 v48, v48, v48
	v_max_f32_e32 v53, v53, v53
	v_max_f32_e32 v49, v49, v49
	v_max_f32_e32 v54, v54, v54
	v_max_f32_e32 v50, v50, v50
	v_max_f32_e32 v55, v55, v55
	v_max_f32_e32 v51, v51, v51
	v_max_f32_e32 v52, 0, v52
	v_max_f32_e32 v48, 0, v48
	v_max_f32_e32 v53, 0, v53
	v_max_f32_e32 v49, 0, v49
	v_max_f32_e32 v54, 0, v54
	v_max_f32_e32 v50, 0, v50
	v_max_f32_e32 v55, 0, v55
	v_max_f32_e32 v51, 0, v51
	v_pk_mul_f32 v[52:53], v[52:53], v[52:53]
	v_pk_mul_f32 v[54:55], v[54:55], v[54:55]
	v_pk_mul_f32 v[48:49], v[48:49], v[48:49]
	v_pk_mul_f32 v[50:51], v[50:51], v[50:51]
.LBB0_490:
	v_cvt_pk_bf16_f32 v52, v52, v53
	v_cvt_pk_bf16_f32 v53, v54, v55
	v_cvt_pk_bf16_f32 v54, v48, v49
	v_mov_b32_e32 v48, v97
	v_mov_b32_e32 v49, v98
	v_mov_b32_e32 v97, v99
	v_pk_add_f32 v[48:49], v[48:49], v[96:97]
	v_cvt_pk_bf16_f32 v55, v50, v51
	global_store_dwordx4 v[70:71], v[52:55], off offset:256 nt
	v_add_f32_e32 v48, v48, v49
	ds_bpermute_b32 v49, v177, v48
	s_waitcnt lgkmcnt(0)
	v_add_f32_e32 v48, v48, v49
	ds_bpermute_b32 v49, v179, v48
	s_waitcnt lgkmcnt(0)
	v_add_f32_e32 v48, v48, v49
	v_fmamk_f32 v48, v48, 0x3a800000, v162
	v_cmp_gt_f32_e32 vcc, s47, v48
	v_mul_f32_e32 v49, 0x4b800000, v48
	s_nop 0
	v_cndmask_b32_e32 v48, v48, v49, vcc
	v_rsq_f32_e32 v48, v48
	s_nop 0
	v_mul_f32_e32 v49, 0x45800000, v48
	v_cndmask_b32_e32 v48, v48, v49, vcc
	v_pk_mul_f32 v[46:47], v[46:47], v[48:49] op_sel_hi:[1,0]
	v_pk_mul_f32 v[44:45], v[44:45], v[48:49] op_sel_hi:[1,0]
	v_pk_mul_f32 v[42:43], v[42:43], v[48:49] op_sel_hi:[1,0]
	v_pk_mul_f32 v[40:41], v[40:41], v[48:49] op_sel_hi:[1,0]
	s_and_b64 vcc, exec, s[38:39]
	s_cbranch_vccnz .LBB0_492
	v_max_f32_e32 v44, v44, v44
	v_max_f32_e32 v40, v40, v40
	v_max_f32_e32 v45, v45, v45
	v_max_f32_e32 v41, v41, v41
	v_max_f32_e32 v46, v46, v46
	v_max_f32_e32 v42, v42, v42
	v_max_f32_e32 v47, v47, v47
	v_max_f32_e32 v43, v43, v43
	v_max_f32_e32 v44, 0, v44
	v_max_f32_e32 v40, 0, v40
	v_max_f32_e32 v45, 0, v45
	v_max_f32_e32 v41, 0, v41
	v_max_f32_e32 v46, 0, v46
	v_max_f32_e32 v42, 0, v42
	v_max_f32_e32 v47, 0, v47
	v_max_f32_e32 v43, 0, v43
	v_pk_mul_f32 v[44:45], v[44:45], v[44:45]
	v_pk_mul_f32 v[46:47], v[46:47], v[46:47]
	v_pk_mul_f32 v[40:41], v[40:41], v[40:41]
	v_pk_mul_f32 v[42:43], v[42:43], v[42:43]
.LBB0_492:
	v_mad_i64_i32 v[50:51], s[44:45], v180, s9, 0
	v_mov_b32_e32 v49, v48
	v_lshl_add_u64 v[50:51], v[50:51], 1, s[70:71]
	v_cvt_pk_bf16_f32 v44, v44, v45
	v_cvt_pk_bf16_f32 v45, v46, v47
	v_cvt_pk_bf16_f32 v46, v40, v41
	v_mov_b32_e32 v40, v48
	v_mov_b32_e32 v41, v48
	v_lshl_add_u64 v[50:51], v[140:141], 1, v[50:51]
	v_pk_mul_f32 v[38:39], v[38:39], v[40:41]
	v_pk_mul_f32 v[36:37], v[36:37], v[48:49]
	v_pk_mul_f32 v[34:35], v[34:35], v[40:41]
	s_and_b64 vcc, exec, s[38:39]
	v_pk_mul_f32 v[32:33], v[32:33], v[48:49]
	v_cvt_pk_bf16_f32 v47, v42, v43
	global_store_dwordx4 v[50:51], v[44:47], off nt
	s_cbranch_vccnz .LBB0_494
	v_max_f32_e32 v36, v36, v36
	v_max_f32_e32 v32, v32, v32
	v_max_f32_e32 v37, v37, v37
	v_max_f32_e32 v33, v33, v33
	v_max_f32_e32 v38, v38, v38
	v_max_f32_e32 v34, v34, v34
	v_max_f32_e32 v39, v39, v39
	v_max_f32_e32 v35, v35, v35
	v_max_f32_e32 v36, 0, v36
	v_max_f32_e32 v32, 0, v32
	v_max_f32_e32 v37, 0, v37
	v_max_f32_e32 v33, 0, v33
	v_max_f32_e32 v38, 0, v38
	v_max_f32_e32 v34, 0, v34
	v_max_f32_e32 v39, 0, v39
	v_max_f32_e32 v35, 0, v35
	v_pk_mul_f32 v[36:37], v[36:37], v[36:37]
	v_pk_mul_f32 v[38:39], v[38:39], v[38:39]
	v_pk_mul_f32 v[32:33], v[32:33], v[32:33]
	v_pk_mul_f32 v[34:35], v[34:35], v[34:35]
.LBB0_494:
	v_cvt_pk_bf16_f32 v36, v36, v37
	v_cvt_pk_bf16_f32 v37, v38, v39
	v_cvt_pk_bf16_f32 v38, v32, v33
	v_mov_b32_e32 v32, v77
	v_mov_b32_e32 v33, v78
	v_mov_b32_e32 v77, v79
	v_pk_add_f32 v[32:33], v[32:33], v[76:77]
	v_cvt_pk_bf16_f32 v39, v34, v35
	global_store_dwordx4 v[50:51], v[36:39], off offset:256 nt
	v_add_f32_e32 v32, v32, v33
	ds_bpermute_b32 v33, v177, v32
	s_waitcnt lgkmcnt(0)
	v_add_f32_e32 v32, v32, v33
	ds_bpermute_b32 v33, v179, v32
	s_waitcnt lgkmcnt(0)
	v_add_f32_e32 v32, v32, v33
	v_fmamk_f32 v32, v32, 0x3a800000, v162
	v_cmp_gt_f32_e32 vcc, s47, v32
	v_mul_f32_e32 v33, 0x4b800000, v32
	s_nop 0
	v_cndmask_b32_e32 v32, v32, v33, vcc
	v_rsq_f32_e32 v32, v32
	s_nop 0
	v_mul_f32_e32 v33, 0x45800000, v32
	v_cndmask_b32_e32 v32, v32, v33, vcc
	v_pk_mul_f32 v[30:31], v[30:31], v[32:33] op_sel_hi:[1,0]
	v_pk_mul_f32 v[28:29], v[28:29], v[32:33] op_sel_hi:[1,0]
	v_pk_mul_f32 v[26:27], v[26:27], v[32:33] op_sel_hi:[1,0]
	v_pk_mul_f32 v[24:25], v[24:25], v[32:33] op_sel_hi:[1,0]
	s_and_b64 vcc, exec, s[38:39]
	s_cbranch_vccnz .LBB0_496
	v_max_f32_e32 v28, v28, v28
	v_max_f32_e32 v24, v24, v24
	v_max_f32_e32 v29, v29, v29
	v_max_f32_e32 v25, v25, v25
	v_max_f32_e32 v30, v30, v30
	v_max_f32_e32 v26, v26, v26
	v_max_f32_e32 v31, v31, v31
	v_max_f32_e32 v27, v27, v27
	v_max_f32_e32 v28, 0, v28
	v_max_f32_e32 v24, 0, v24
	v_max_f32_e32 v29, 0, v29
	v_max_f32_e32 v25, 0, v25
	v_max_f32_e32 v30, 0, v30
	v_max_f32_e32 v26, 0, v26
	v_max_f32_e32 v31, 0, v31
	v_max_f32_e32 v27, 0, v27
	v_pk_mul_f32 v[28:29], v[28:29], v[28:29]
	v_pk_mul_f32 v[30:31], v[30:31], v[30:31]
	v_pk_mul_f32 v[24:25], v[24:25], v[24:25]
	v_pk_mul_f32 v[26:27], v[26:27], v[26:27]
; #define PG8_BAR __builtin_amdgcn_s_barrier()
; DI unsigned pk(float lo, float hi) { return pg8::cvt_pk_bf16(lo, hi); }
; template <class Epi, class Sched, bool ALIGN_EPI = false, bool SP2 = false>
; __device__ __forceinline__ void gemm_phase(PG8_LAS unsigned char* lds, const Gemm g, const Sched& S, const Epi& E) {
;     ...
;         if (!has_next) break;
; #pragma unroll
;         for (int a = 0; a < 2; ++a)
; #pragma unroll
;             for (int b = 0; b < 2; ++b)
; #pragma unroll
;                 for (int m = 0; m < 4; ++m)
; #pragma unroll
;                     for (int n = 0; n < 2; ++n) acc[a][b][m][n] = (f32x4){0.f, 0.f, 0.f, 0.f};
;         cur = nxt; cA = nA; cB = nB; ++ui;
;         if constexpr (ALIGN_EPI) { if (wr == 1) PG8_BAR; }
;     DI void operator()(const f32x4 (&acc)[2][2][4][2], const pg8::Unit& u, int wr, int wc, int fr, int fq) const {
;     ...
;                 const int row = row0 + ai * 128 + m * 16;
;                 const f32x4 p = pp[ai * 4 + m];
;                 float s = (p[0] + p[1]) + (p[2] + p[3]);
;                 s += __shfl_xor(s, 16); s += __shfl_xor(s, 32);
;                 const float rstd = rsqrtf(s * (1.0f / D) + EPS);
;                 bf16_t* rowp = O + (size_t)row * ldc + col0;
; #pragma unroll
;                 for (int bj = 0; bj < 2; ++bj) {
;                     f32x4 v0 = acc[ai][bj][m][0] * rstd, v1 = acc[ai][bj][m][1] * rstd;
;                     if (act) {
; #pragma unroll
;                         for (int k = 0; k < 4; ++k) { float a = fmaxf(v0[k], 0.f), b = fmaxf(v1[k], 0.f); v0[k] = a * a; v1[k] = b * b; }
;                     }
;                     u32x4 w; w.x = pk(v0[0], v0[1]); w.y = pk(v0[2], v0[3]); w.z = pk(v1[0], v1[1]); w.w = pk(v1[2], v1[3]);
;                     *(u32x4*)(rowp + bj * 128) = w;
;                 }
.LBB0_496:
	v_mad_i64_i32 v[34:35], s[44:45], v178, s9, 0
	v_mov_b32_e32 v33, v32
	v_lshl_add_u64 v[34:35], v[34:35], 1, s[70:71]
	v_cvt_pk_bf16_f32 v28, v28, v29
	v_cvt_pk_bf16_f32 v29, v30, v31
	v_cvt_pk_bf16_f32 v30, v24, v25
	v_mov_b32_e32 v24, v32
	v_mov_b32_e32 v25, v32
	v_lshl_add_u64 v[34:35], v[140:141], 1, v[34:35]
	v_pk_mul_f32 v[22:23], v[22:23], v[24:25]
	v_pk_mul_f32 v[20:21], v[20:21], v[32:33]
	v_pk_mul_f32 v[18:19], v[18:19], v[24:25]
	s_and_b64 vcc, exec, s[38:39]
	v_pk_mul_f32 v[16:17], v[16:17], v[32:33]
	v_cvt_pk_bf16_f32 v31, v26, v27
	global_store_dwordx4 v[34:35], v[28:31], off nt
	s_cbranch_vccnz .LBB0_498
	v_max_f32_e32 v20, v20, v20
	v_max_f32_e32 v16, v16, v16
	v_max_f32_e32 v21, v21, v21
	v_max_f32_e32 v17, v17, v17
	v_max_f32_e32 v22, v22, v22
	v_max_f32_e32 v18, v18, v18
	v_max_f32_e32 v23, v23, v23
	v_max_f32_e32 v19, v19, v19
	v_max_f32_e32 v20, 0, v20
	v_max_f32_e32 v16, 0, v16
	v_max_f32_e32 v21, 0, v21
	v_max_f32_e32 v17, 0, v17
	v_max_f32_e32 v22, 0, v22
	v_max_f32_e32 v18, 0, v18
	v_max_f32_e32 v23, 0, v23
	v_max_f32_e32 v19, 0, v19
	v_pk_mul_f32 v[20:21], v[20:21], v[20:21]
	v_pk_mul_f32 v[22:23], v[22:23], v[22:23]
	v_pk_mul_f32 v[16:17], v[16:17], v[16:17]
	v_pk_mul_f32 v[18:19], v[18:19], v[18:19]
.LBB0_498:
	v_cvt_pk_bf16_f32 v20, v20, v21
	v_cvt_pk_bf16_f32 v21, v22, v23
	v_cvt_pk_bf16_f32 v22, v16, v17
	v_mov_b32_e32 v16, v57
	v_mov_b32_e32 v17, v58
	v_mov_b32_e32 v57, v59
	v_pk_add_f32 v[16:17], v[16:17], v[56:57]
	v_cvt_pk_bf16_f32 v23, v18, v19
	global_store_dwordx4 v[34:35], v[20:23], off offset:256 nt
	v_add_f32_e32 v16, v16, v17
	ds_bpermute_b32 v17, v177, v16
	s_waitcnt lgkmcnt(0)
	v_add_f32_e32 v16, v16, v17
	ds_bpermute_b32 v17, v179, v16
	s_waitcnt lgkmcnt(0)
	v_add_f32_e32 v16, v16, v17
	v_fmamk_f32 v16, v16, 0x3a800000, v162
	v_cmp_gt_f32_e32 vcc, s47, v16
	v_mul_f32_e32 v17, 0x4b800000, v16
	s_nop 0
	v_cndmask_b32_e32 v16, v16, v17, vcc
	v_rsq_f32_e32 v16, v16
	s_nop 0
	v_mul_f32_e32 v17, 0x45800000, v16
	v_cndmask_b32_e32 v16, v16, v17, vcc
	v_pk_mul_f32 v[14:15], v[14:15], v[16:17] op_sel_hi:[1,0]
	v_pk_mul_f32 v[12:13], v[12:13], v[16:17] op_sel_hi:[1,0]
	v_pk_mul_f32 v[10:11], v[10:11], v[16:17] op_sel_hi:[1,0]
	v_pk_mul_f32 v[8:9], v[8:9], v[16:17] op_sel_hi:[1,0]
	s_and_b64 vcc, exec, s[38:39]
	s_cbranch_vccnz .LBB0_500
	v_max_f32_e32 v12, v12, v12
	v_max_f32_e32 v8, v8, v8
	v_max_f32_e32 v13, v13, v13
	v_max_f32_e32 v9, v9, v9
	v_max_f32_e32 v14, v14, v14
	v_max_f32_e32 v10, v10, v10
	v_max_f32_e32 v15, v15, v15
	v_max_f32_e32 v11, v11, v11
	v_max_f32_e32 v12, 0, v12
	v_max_f32_e32 v8, 0, v8
	v_max_f32_e32 v13, 0, v13
	v_max_f32_e32 v9, 0, v9
	v_max_f32_e32 v14, 0, v14
	v_max_f32_e32 v10, 0, v10
	v_max_f32_e32 v15, 0, v15
	v_max_f32_e32 v11, 0, v11
	v_pk_mul_f32 v[12:13], v[12:13], v[12:13]
	v_pk_mul_f32 v[14:15], v[14:15], v[14:15]
	v_pk_mul_f32 v[8:9], v[8:9], v[8:9]
	v_pk_mul_f32 v[10:11], v[10:11], v[10:11]
.LBB0_500:
	v_mad_i64_i32 v[18:19], s[44:45], v176, s9, 0
	v_mov_b32_e32 v17, v16
	v_lshl_add_u64 v[18:19], v[18:19], 1, s[70:71]
	v_cvt_pk_bf16_f32 v12, v12, v13
	v_cvt_pk_bf16_f32 v13, v14, v15
	v_cvt_pk_bf16_f32 v14, v8, v9
	v_mov_b32_e32 v8, v16
	v_mov_b32_e32 v9, v16
	v_lshl_add_u64 v[18:19], v[140:141], 1, v[18:19]
	v_pk_mul_f32 v[6:7], v[6:7], v[8:9]
	v_pk_mul_f32 v[4:5], v[4:5], v[16:17]
	v_pk_mul_f32 v[2:3], v[2:3], v[8:9]
	s_and_b64 vcc, exec, s[38:39]
	v_pk_mul_f32 v[0:1], v[0:1], v[16:17]
	v_cvt_pk_bf16_f32 v15, v10, v11
	global_store_dwordx4 v[18:19], v[12:15], off nt
	s_cbranch_vccnz .LBB0_502
	v_max_f32_e32 v4, v4, v4
	v_max_f32_e32 v0, v0, v0
	v_max_f32_e32 v5, v5, v5
	v_max_f32_e32 v1, v1, v1
	v_max_f32_e32 v6, v6, v6
	v_max_f32_e32 v2, v2, v2
	v_max_f32_e32 v7, v7, v7
	v_max_f32_e32 v3, v3, v3
	v_max_f32_e32 v4, 0, v4
	v_max_f32_e32 v0, 0, v0
	v_max_f32_e32 v5, 0, v5
	v_max_f32_e32 v1, 0, v1
	v_max_f32_e32 v6, 0, v6
	v_max_f32_e32 v2, 0, v2
	v_max_f32_e32 v7, 0, v7
	v_max_f32_e32 v3, 0, v3
	v_pk_mul_f32 v[4:5], v[4:5], v[4:5]
	v_pk_mul_f32 v[6:7], v[6:7], v[6:7]
	v_pk_mul_f32 v[0:1], v[0:1], v[0:1]
	v_pk_mul_f32 v[2:3], v[2:3], v[2:3]
.LBB0_502:
	s_andn2_b64 vcc, exec, s[36:37]
	s_mov_b64 s[36:37], -1
	v_cvt_pk_bf16_f32 v4, v4, v5
	v_cvt_pk_bf16_f32 v5, v6, v7
	v_cvt_pk_bf16_f32 v6, v0, v1
	v_cvt_pk_bf16_f32 v7, v2, v3
	global_store_dwordx4 v[18:19], v[4:7], off offset:256 nt
	s_cbranch_vccnz .LBB0_463
	s_andn2_b64 vcc, exec, s[2:3]
	s_cbranch_vccnz .LBB0_462
	s_barrier
	s_branch .LBB0_462

; __global__ void __launch_bounds__(512, 2) hybrid_fwd(Args a) {
	.amdhsa_kernel _Z10hybrid_fwd4Args
		.amdhsa_group_segment_fixed_size 0
		.amdhsa_private_segment_fixed_size 0
		.amdhsa_kernarg_size 392
		.amdhsa_user_sgpr_count 2
		.amdhsa_user_sgpr_dispatch_ptr 0
		.amdhsa_user_sgpr_queue_ptr 0
		.amdhsa_user_sgpr_kernarg_segment_ptr 1
		.amdhsa_user_sgpr_dispatch_id 0
		.amdhsa_user_sgpr_kernarg_preload_length 0
		.amdhsa_user_sgpr_kernarg_preload_offset 0
		.amdhsa_user_sgpr_private_segment_size 0
		.amdhsa_uses_dynamic_stack 0
		.amdhsa_enable_private_segment 0
		.amdhsa_system_sgpr_workgroup_id_x 1
		.amdhsa_system_sgpr_workgroup_id_y 0
		.amdhsa_system_sgpr_workgroup_id_z 0
		.amdhsa_system_sgpr_workgroup_info 0
		.amdhsa_system_vgpr_workitem_id 2
		.amdhsa_next_free_vgpr 251
		.amdhsa_next_free_sgpr 102
		.amdhsa_accum_offset 252
		.amdhsa_reserve_vcc 1
		.amdhsa_float_round_mode_32 0
		.amdhsa_float_round_mode_16_64 0
		.amdhsa_float_denorm_mode_32 3
		.amdhsa_float_denorm_mode_16_64 3
		.amdhsa_dx10_clamp 1
		.amdhsa_ieee_mode 1
		.amdhsa_fp16_overflow 0
		.amdhsa_tg_split 0
		.amdhsa_exception_fp_ieee_invalid_op 0
		.amdhsa_exception_fp_denorm_src 0
		.amdhsa_exception_fp_ieee_div_zero 0
		.amdhsa_exception_fp_ieee_overflow 0
		.amdhsa_exception_fp_ieee_underflow 0
		.amdhsa_exception_fp_ieee_inexact 0
		.amdhsa_exception_int_div_zero 0
	.end_amdhsa_kernel
